# E19: A-fragment ds_reads of the next load segment issued between the 4 trailing MFMAs after the early barrier (MFMA/LDS interleave)
# speedup vs baseline: 1.0169x; 1.0008x over previous
.LBB0_225:
	ds_read_b128 v[128:131], v157
	ds_read_b128 v[132:135], v157 offset:1024
	ds_read_b128 v[146:149], v157 offset:2048
	ds_read_b128 v[164:167], v157 offset:3072
	ds_read_b128 v[168:171], v159
	ds_read_b128 v[172:175], v159 offset:1024
	ds_read_b128 v[176:179], v159 offset:2048
	ds_read_b128 v[180:183], v159 offset:3072
	s_add_u32 s36, s22, 0xfff80080
	s_addc_u32 s37, s23, -1
	s_cmp_eq_u32 s78, 28
	s_cselect_b32 s81, s5, s37
	s_cselect_b32 s80, s14, s36
	s_cselect_b32 vcc_hi, s20, s45
	s_cselect_b32 vcc_lo, s21, s24
	s_add_i32 m0, s77, 0xc000
	ds_read_b128 v[184:187], v161
	ds_read_b128 v[188:191], v161 offset:1024
	ds_read_b128 v[192:195], v161 offset:2048
	ds_read_b128 v[196:199], v161 offset:3072
	ds_read_b128 v[200:203], v161 offset:4096
	ds_read_b128 v[204:207], v161 offset:5120
	ds_read_b128 v[208:211], v161 offset:6144
	ds_read_b128 v[212:215], v161 offset:7168
	global_load_lds_dwordx4 v140, s[22:23]
	s_add_i32 m0, s77, 0xe000
	s_nop 0
	s_add_u32 s98, s22, s6
	s_addc_u32 s99, s23, s7
	global_load_lds_dwordx4 v140, s[98:99]
	s_waitcnt vmcnt(8)
	s_waitcnt lgkmcnt(0)
	s_barrier
	s_setprio 1
	s_waitcnt lgkmcnt(0)
	v_mfma_i32_16x16x64_i8 v[0:3], v[128:131], v[184:187], v[0:3]
	v_mfma_i32_16x16x64_i8 v[0:3], v[132:135], v[188:191], v[0:3]
	v_mfma_i32_16x16x64_i8 v[56:59], v[146:149], v[184:187], v[56:59]
	v_mfma_i32_16x16x64_i8 v[56:59], v[164:167], v[188:191], v[56:59]
	v_mfma_i32_16x16x64_i8 v[4:7], v[128:131], v[192:195], v[4:7]
	v_mfma_i32_16x16x64_i8 v[4:7], v[132:135], v[196:199], v[4:7]
	v_mfma_i32_16x16x64_i8 v[52:55], v[146:149], v[192:195], v[52:55]
	v_mfma_i32_16x16x64_i8 v[52:55], v[164:167], v[196:199], v[52:55]
	v_mfma_i32_16x16x64_i8 v[12:15], v[128:131], v[200:203], v[12:15]
	v_mfma_i32_16x16x64_i8 v[12:15], v[132:135], v[204:207], v[12:15]
	v_mfma_i32_16x16x64_i8 v[48:51], v[146:149], v[200:203], v[48:51]
	v_mfma_i32_16x16x64_i8 v[48:51], v[164:167], v[204:207], v[48:51]
	v_mfma_i32_16x16x64_i8 v[8:11], v[128:131], v[208:211], v[8:11]
	v_mfma_i32_16x16x64_i8 v[8:11], v[132:135], v[212:215], v[8:11]
	v_mfma_i32_16x16x64_i8 v[44:47], v[146:149], v[208:211], v[44:47]
	v_mfma_i32_16x16x64_i8 v[44:47], v[164:167], v[212:215], v[44:47]
	s_setprio 0
	s_setprio 1
	v_mfma_i32_16x16x64_i8 v[88:91], v[168:171], v[184:187], v[88:91]
	v_mfma_i32_16x16x64_i8 v[88:91], v[172:175], v[188:191], v[88:91]
	v_mfma_i32_16x16x64_i8 v[120:123], v[176:179], v[184:187], v[120:123]
	v_mfma_i32_16x16x64_i8 v[120:123], v[180:183], v[188:191], v[120:123]
	v_mfma_i32_16x16x64_i8 v[84:87], v[168:171], v[192:195], v[84:87]
	v_mfma_i32_16x16x64_i8 v[84:87], v[172:175], v[196:199], v[84:87]
	v_mfma_i32_16x16x64_i8 v[116:119], v[176:179], v[192:195], v[116:119]
	v_mfma_i32_16x16x64_i8 v[116:119], v[180:183], v[196:199], v[116:119]
	v_mfma_i32_16x16x64_i8 v[80:83], v[168:171], v[200:203], v[80:83]
	v_mfma_i32_16x16x64_i8 v[80:83], v[172:175], v[204:207], v[80:83]
	v_mfma_i32_16x16x64_i8 v[112:115], v[176:179], v[200:203], v[112:115]
	v_mfma_i32_16x16x64_i8 v[112:115], v[180:183], v[204:207], v[112:115]
	s_setprio 2
	s_barrier
	v_mfma_i32_16x16x64_i8 v[76:79], v[168:171], v[208:211], v[76:79]
	ds_read_b128 v[184:187], v161 offset:16384
	ds_read_b128 v[188:191], v161 offset:17408
	v_mfma_i32_16x16x64_i8 v[76:79], v[172:175], v[212:215], v[76:79]
	ds_read_b128 v[192:195], v161 offset:18432
	ds_read_b128 v[196:199], v161 offset:19456
	v_mfma_i32_16x16x64_i8 v[108:111], v[176:179], v[208:211], v[108:111]
	ds_read_b128 v[200:203], v161 offset:20480
	ds_read_b128 v[204:207], v161 offset:21504
	v_mfma_i32_16x16x64_i8 v[108:111], v[180:183], v[212:215], v[108:111]
	s_setprio 0
	s_add_i32 s36, s86, s63
	s_mov_b32 m0, s36
	ds_read_b128 v[208:211], v161 offset:22528
	ds_read_b128 v[212:215], v161 offset:23552
	global_load_lds_dwordx4 v138, vcc
	s_add_i32 m0, s36, 0x2000
	s_add_i32 s36, s87, s63
	s_add_u32 s98, vcc_lo, s6
	s_addc_u32 s99, vcc_hi, s7
	global_load_lds_dwordx4 v138, s[98:99]
	s_mov_b32 m0, s36
	s_nop 0
	s_add_u32 s98, vcc_lo, s8
	s_addc_u32 s99, vcc_hi, s9
	global_load_lds_dwordx4 v138, s[98:99]
	s_add_i32 m0, s36, 0x2000
	s_nop 0
	s_add_u32 s98, vcc_lo, s10
	s_addc_u32 s99, vcc_hi, s11
	global_load_lds_dwordx4 v138, s[98:99]
	s_mov_b32 m0, s77
	s_nop 0
	global_load_lds_dwordx4 v136, s[80:81]
	s_mov_b32 m0, s97
	s_nop 0
	s_add_u32 s98, s80, s6
	s_addc_u32 s99, s81, s7
	global_load_lds_dwordx4 v136, s[98:99]
	s_waitcnt vmcnt(8)
	s_waitcnt lgkmcnt(0)
	s_barrier
	s_setprio 1
	s_waitcnt lgkmcnt(0)
	v_mfma_i32_16x16x64_i8 v[20:23], v[128:131], v[184:187], v[20:23]
	v_mfma_i32_16x16x64_i8 v[20:23], v[132:135], v[188:191], v[20:23]
	v_mfma_i32_16x16x64_i8 v[40:43], v[146:149], v[184:187], v[40:43]
	v_mfma_i32_16x16x64_i8 v[40:43], v[164:167], v[188:191], v[40:43]
	v_mfma_i32_16x16x64_i8 v[16:19], v[128:131], v[192:195], v[16:19]
	v_mfma_i32_16x16x64_i8 v[16:19], v[132:135], v[196:199], v[16:19]
	v_mfma_i32_16x16x64_i8 v[36:39], v[146:149], v[192:195], v[36:39]
	v_mfma_i32_16x16x64_i8 v[36:39], v[164:167], v[196:199], v[36:39]
	v_mfma_i32_16x16x64_i8 v[24:27], v[128:131], v[200:203], v[24:27]
	v_mfma_i32_16x16x64_i8 v[24:27], v[132:135], v[204:207], v[24:27]
	v_mfma_i32_16x16x64_i8 v[32:35], v[146:149], v[200:203], v[32:35]
	v_mfma_i32_16x16x64_i8 v[32:35], v[164:167], v[204:207], v[32:35]
	v_mfma_i32_16x16x64_i8 v[28:31], v[128:131], v[208:211], v[28:31]
	v_mfma_i32_16x16x64_i8 v[28:31], v[132:135], v[212:215], v[28:31]
	v_mfma_i32_16x16x64_i8 v[60:63], v[146:149], v[208:211], v[60:63]
	v_mfma_i32_16x16x64_i8 v[60:63], v[164:167], v[212:215], v[60:63]
	s_setprio 0
	s_setprio 1
	v_mfma_i32_16x16x64_i8 v[72:75], v[168:171], v[184:187], v[72:75]
	v_mfma_i32_16x16x64_i8 v[72:75], v[172:175], v[188:191], v[72:75]
	v_mfma_i32_16x16x64_i8 v[104:107], v[176:179], v[184:187], v[104:107]
	v_mfma_i32_16x16x64_i8 v[104:107], v[180:183], v[188:191], v[104:107]
	v_mfma_i32_16x16x64_i8 v[68:71], v[168:171], v[192:195], v[68:71]
	v_mfma_i32_16x16x64_i8 v[68:71], v[172:175], v[196:199], v[68:71]
	v_mfma_i32_16x16x64_i8 v[100:103], v[176:179], v[192:195], v[100:103]
	v_mfma_i32_16x16x64_i8 v[100:103], v[180:183], v[196:199], v[100:103]
	v_mfma_i32_16x16x64_i8 v[64:67], v[168:171], v[200:203], v[64:67]
	v_mfma_i32_16x16x64_i8 v[64:67], v[172:175], v[204:207], v[64:67]
	v_mfma_i32_16x16x64_i8 v[96:99], v[176:179], v[200:203], v[96:99]
	v_mfma_i32_16x16x64_i8 v[96:99], v[180:183], v[204:207], v[96:99]
	s_setprio 2
	s_barrier
	v_mfma_i32_16x16x64_i8 v[92:95], v[168:171], v[208:211], v[92:95]
	ds_read_b128 v[184:187], v161 offset:32768
	ds_read_b128 v[188:191], v161 offset:33792
	v_mfma_i32_16x16x64_i8 v[92:95], v[172:175], v[212:215], v[92:95]
	ds_read_b128 v[192:195], v161 offset:34816
	ds_read_b128 v[196:199], v161 offset:35840
	v_mfma_i32_16x16x64_i8 v[124:127], v[176:179], v[208:211], v[124:127]
	ds_read_b128 v[200:203], v161 offset:36864
	ds_read_b128 v[204:207], v161 offset:37888
	v_mfma_i32_16x16x64_i8 v[124:127], v[180:183], v[212:215], v[124:127]
	s_setprio 0
	s_add_i32 s36, 0, 0x18000
	v_add_u32_e32 v152, s36, v153
	s_add_i32 s37, 0, 0x1c000
	ds_read_b128 v[128:131], v152
	ds_read_b128 v[132:135], v152 offset:1024
	ds_read_b128 v[146:149], v152 offset:2048
	ds_read_b128 v[164:167], v152 offset:3072
	v_add_u32_e32 v152, s37, v153
	ds_read_b128 v[168:171], v152
	ds_read_b128 v[172:175], v152 offset:1024
	ds_read_b128 v[176:179], v152 offset:2048
	ds_read_b128 v[180:183], v152 offset:3072
	s_mov_b32 m0, s33
	ds_read_b128 v[208:211], v161 offset:38912
	ds_read_b128 v[212:215], v161 offset:39936
	s_add_u32 s98, s80, s8
	s_addc_u32 s99, s81, s9
	global_load_lds_dwordx4 v136, s[98:99]
	s_mov_b32 m0, s93
	s_nop 0
	s_add_u32 s98, s80, s10
	s_addc_u32 s99, s81, s11
	global_load_lds_dwordx4 v136, s[98:99]
	s_waitcnt vmcnt(8)
	s_waitcnt lgkmcnt(0)
	s_barrier
	s_setprio 1
	s_waitcnt lgkmcnt(0)
	v_mfma_i32_16x16x64_i8 v[0:3], v[128:131], v[184:187], v[0:3]
	v_mfma_i32_16x16x64_i8 v[0:3], v[132:135], v[188:191], v[0:3]
	v_mfma_i32_16x16x64_i8 v[56:59], v[146:149], v[184:187], v[56:59]
	v_mfma_i32_16x16x64_i8 v[56:59], v[164:167], v[188:191], v[56:59]
	v_mfma_i32_16x16x64_i8 v[4:7], v[128:131], v[192:195], v[4:7]
	v_mfma_i32_16x16x64_i8 v[4:7], v[132:135], v[196:199], v[4:7]
	v_mfma_i32_16x16x64_i8 v[52:55], v[146:149], v[192:195], v[52:55]
	v_mfma_i32_16x16x64_i8 v[52:55], v[164:167], v[196:199], v[52:55]
	v_mfma_i32_16x16x64_i8 v[12:15], v[128:131], v[200:203], v[12:15]
	v_mfma_i32_16x16x64_i8 v[12:15], v[132:135], v[204:207], v[12:15]
	v_mfma_i32_16x16x64_i8 v[48:51], v[146:149], v[200:203], v[48:51]
	v_mfma_i32_16x16x64_i8 v[48:51], v[164:167], v[204:207], v[48:51]
	v_mfma_i32_16x16x64_i8 v[8:11], v[128:131], v[208:211], v[8:11]
	v_mfma_i32_16x16x64_i8 v[8:11], v[132:135], v[212:215], v[8:11]
	v_mfma_i32_16x16x64_i8 v[44:47], v[146:149], v[208:211], v[44:47]
	v_mfma_i32_16x16x64_i8 v[44:47], v[164:167], v[212:215], v[44:47]
	s_setprio 0
	s_setprio 1
	v_mfma_i32_16x16x64_i8 v[88:91], v[168:171], v[184:187], v[88:91]
	v_mfma_i32_16x16x64_i8 v[88:91], v[172:175], v[188:191], v[88:91]
	v_mfma_i32_16x16x64_i8 v[120:123], v[176:179], v[184:187], v[120:123]
	v_mfma_i32_16x16x64_i8 v[120:123], v[180:183], v[188:191], v[120:123]
	v_mfma_i32_16x16x64_i8 v[84:87], v[168:171], v[192:195], v[84:87]
	v_mfma_i32_16x16x64_i8 v[84:87], v[172:175], v[196:199], v[84:87]
	v_mfma_i32_16x16x64_i8 v[116:119], v[176:179], v[192:195], v[116:119]
	v_mfma_i32_16x16x64_i8 v[116:119], v[180:183], v[196:199], v[116:119]
	v_mfma_i32_16x16x64_i8 v[80:83], v[168:171], v[200:203], v[80:83]
	v_mfma_i32_16x16x64_i8 v[80:83], v[172:175], v[204:207], v[80:83]
	v_mfma_i32_16x16x64_i8 v[112:115], v[176:179], v[200:203], v[112:115]
	v_mfma_i32_16x16x64_i8 v[112:115], v[180:183], v[204:207], v[112:115]
	s_setprio 2
	s_barrier
	v_mfma_i32_16x16x64_i8 v[76:79], v[168:171], v[208:211], v[76:79]
	ds_read_b128 v[184:187], v161 offset:49152
	ds_read_b128 v[188:191], v161 offset:50176
	v_mfma_i32_16x16x64_i8 v[76:79], v[172:175], v[212:215], v[76:79]
	ds_read_b128 v[192:195], v161 offset:51200
	ds_read_b128 v[196:199], v161 offset:52224
	v_mfma_i32_16x16x64_i8 v[108:111], v[176:179], v[208:211], v[108:111]
	ds_read_b128 v[200:203], v161 offset:53248
	ds_read_b128 v[204:207], v161 offset:54272
	v_mfma_i32_16x16x64_i8 v[108:111], v[180:183], v[212:215], v[108:111]
	s_setprio 0
	s_add_i32 s36, s36, s63
	s_mov_b32 m0, s36
	ds_read_b128 v[208:211], v161 offset:55296
	ds_read_b128 v[212:215], v161 offset:56320
	s_add_u32 s98, vcc_lo, s46
	s_addc_u32 s99, vcc_hi, s47
	global_load_lds_dwordx4 v138, s[98:99]
	s_add_i32 m0, s36, 0x2000
	s_add_i32 s36, s37, s63
	s_add_u32 s98, vcc_lo, s48
	s_addc_u32 s99, vcc_hi, s49
	global_load_lds_dwordx4 v138, s[98:99]
	s_mov_b32 m0, s36
	s_add_u32 s98, vcc_lo, s54
	s_addc_u32 s99, vcc_hi, s55
	global_load_lds_dwordx4 v138, s[98:99]
	s_add_i32 m0, s36, 0x2000
	s_nop 0
	s_add_u32 s98, vcc_lo, s56
	s_addc_u32 s99, vcc_hi, s57
	global_load_lds_dwordx4 v138, s[98:99]
	s_mov_b32 m0, s95
	s_nop 0
	s_add_u32 s98, s80, s46
	s_addc_u32 s99, s81, s47
	global_load_lds_dwordx4 v136, s[98:99]
	s_mov_b32 m0, s82
	s_nop 0
	s_add_u32 s98, s80, s48
	s_addc_u32 s99, s81, s49
	global_load_lds_dwordx4 v136, s[98:99]
	s_waitcnt vmcnt(8)
	s_waitcnt lgkmcnt(0)
	s_barrier
	s_setprio 1
	s_waitcnt lgkmcnt(0)
	v_mfma_i32_16x16x64_i8 v[20:23], v[128:131], v[184:187], v[20:23]
	v_mfma_i32_16x16x64_i8 v[20:23], v[132:135], v[188:191], v[20:23]
	v_mfma_i32_16x16x64_i8 v[40:43], v[146:149], v[184:187], v[40:43]
	v_mfma_i32_16x16x64_i8 v[40:43], v[164:167], v[188:191], v[40:43]
	v_mfma_i32_16x16x64_i8 v[16:19], v[128:131], v[192:195], v[16:19]
	v_mfma_i32_16x16x64_i8 v[16:19], v[132:135], v[196:199], v[16:19]
	v_mfma_i32_16x16x64_i8 v[36:39], v[146:149], v[192:195], v[36:39]
	v_mfma_i32_16x16x64_i8 v[36:39], v[164:167], v[196:199], v[36:39]
	v_mfma_i32_16x16x64_i8 v[24:27], v[128:131], v[200:203], v[24:27]
	v_mfma_i32_16x16x64_i8 v[24:27], v[132:135], v[204:207], v[24:27]
	v_mfma_i32_16x16x64_i8 v[32:35], v[146:149], v[200:203], v[32:35]
	v_mfma_i32_16x16x64_i8 v[32:35], v[164:167], v[204:207], v[32:35]
	v_mfma_i32_16x16x64_i8 v[28:31], v[128:131], v[208:211], v[28:31]
	v_mfma_i32_16x16x64_i8 v[28:31], v[132:135], v[212:215], v[28:31]
	v_mfma_i32_16x16x64_i8 v[60:63], v[146:149], v[208:211], v[60:63]
	v_mfma_i32_16x16x64_i8 v[60:63], v[164:167], v[212:215], v[60:63]
	s_setprio 0
	s_setprio 1
	v_mfma_i32_16x16x64_i8 v[72:75], v[168:171], v[184:187], v[72:75]
	v_mfma_i32_16x16x64_i8 v[72:75], v[172:175], v[188:191], v[72:75]
	v_mfma_i32_16x16x64_i8 v[104:107], v[176:179], v[184:187], v[104:107]
	v_mfma_i32_16x16x64_i8 v[104:107], v[180:183], v[188:191], v[104:107]
	v_mfma_i32_16x16x64_i8 v[68:71], v[168:171], v[192:195], v[68:71]
	v_mfma_i32_16x16x64_i8 v[68:71], v[172:175], v[196:199], v[68:71]
	v_mfma_i32_16x16x64_i8 v[100:103], v[176:179], v[192:195], v[100:103]
	v_mfma_i32_16x16x64_i8 v[100:103], v[180:183], v[196:199], v[100:103]
	v_mfma_i32_16x16x64_i8 v[64:67], v[168:171], v[200:203], v[64:67]
	v_mfma_i32_16x16x64_i8 v[64:67], v[172:175], v[204:207], v[64:67]
	v_mfma_i32_16x16x64_i8 v[96:99], v[176:179], v[200:203], v[96:99]
	v_mfma_i32_16x16x64_i8 v[96:99], v[180:183], v[204:207], v[96:99]
	s_setprio 2
	s_barrier
	v_mfma_i32_16x16x64_i8 v[92:95], v[168:171], v[208:211], v[92:95]
	v_mfma_i32_16x16x64_i8 v[92:95], v[172:175], v[212:215], v[92:95]
	v_mfma_i32_16x16x64_i8 v[124:127], v[176:179], v[208:211], v[124:127]
	v_mfma_i32_16x16x64_i8 v[124:127], v[180:183], v[212:215], v[124:127]
	s_setprio 0
	s_add_i32 s78, s78, 2
	s_add_u32 s24, s24, 0x100
	s_addc_u32 s45, s45, 0
	s_add_u32 s22, s22, 0x100
	s_addc_u32 s23, s23, 0
	s_cmp_gt_u32 s78, 29
	s_cbranch_scc0 .LBB0_225
	v_readlane_b32 s14, v250, 9
	v_readlane_b32 s15, v250, 10
	s_and_b64 vcc, exec, s[14:15]
	s_cbranch_vccz .LBB0_228
	s_barrier

.LBB0_298:
	ds_read_b128 v[128:131], v153
	ds_read_b128 v[132:135], v153 offset:1024
	ds_read_b128 v[146:149], v153 offset:2048
	ds_read_b128 v[158:161], v153 offset:3072
	ds_read_b128 v[162:165], v154
	ds_read_b128 v[166:169], v154 offset:1024
	ds_read_b128 v[170:173], v154 offset:2048
	ds_read_b128 v[174:177], v154 offset:3072
	s_add_u32 s36, s78, 0xfff00080
	s_addc_u32 s37, s79, -1
	s_cmp_eq_u32 s81, 60
	s_cselect_b32 s97, s5, s37
	s_cselect_b32 s96, s14, s36
	s_cselect_b32 vcc_hi, s20, s80
	s_cselect_b32 vcc_lo, s21, s22
	s_add_i32 m0, s33, 0xc000
	ds_read_b128 v[178:181], v155
	ds_read_b128 v[182:185], v155 offset:1024
	ds_read_b128 v[186:189], v155 offset:2048
	ds_read_b128 v[190:193], v155 offset:3072
	ds_read_b128 v[194:197], v155 offset:4096
	ds_read_b128 v[198:201], v155 offset:5120
	ds_read_b128 v[202:205], v155 offset:6144
	ds_read_b128 v[206:209], v155 offset:7168
	global_load_lds_dwordx4 v140, s[78:79]
	s_add_i32 m0, s33, 0xe000
	s_nop 0
	s_add_u32 s98, s78, s0
	s_addc_u32 s99, s79, s1
	global_load_lds_dwordx4 v140, s[98:99]
	s_waitcnt vmcnt(8)
	s_waitcnt lgkmcnt(0)
	s_barrier
	s_setprio 1
	s_waitcnt lgkmcnt(0)
	v_mfma_f32_16x16x32_bf16 v[124:127], v[128:131], v[178:181], v[124:127]
	v_mfma_f32_16x16x32_bf16 v[124:127], v[132:135], v[182:185], v[124:127]
	v_mfma_f32_16x16x32_bf16 v[120:123], v[146:149], v[178:181], v[120:123]
	v_mfma_f32_16x16x32_bf16 v[120:123], v[158:161], v[182:185], v[120:123]
	v_mfma_f32_16x16x32_bf16 v[112:115], v[128:131], v[186:189], v[112:115]
	v_mfma_f32_16x16x32_bf16 v[112:115], v[132:135], v[190:193], v[112:115]
	v_mfma_f32_16x16x32_bf16 v[108:111], v[146:149], v[186:189], v[108:111]
	v_mfma_f32_16x16x32_bf16 v[108:111], v[158:161], v[190:193], v[108:111]
	v_mfma_f32_16x16x32_bf16 v[100:103], v[128:131], v[194:197], v[100:103]
	v_mfma_f32_16x16x32_bf16 v[100:103], v[132:135], v[198:201], v[100:103]
	v_mfma_f32_16x16x32_bf16 v[92:95], v[146:149], v[194:197], v[92:95]
	v_mfma_f32_16x16x32_bf16 v[92:95], v[158:161], v[198:201], v[92:95]
	v_mfma_f32_16x16x32_bf16 v[84:87], v[128:131], v[202:205], v[84:87]
	v_mfma_f32_16x16x32_bf16 v[84:87], v[132:135], v[206:209], v[84:87]
	v_mfma_f32_16x16x32_bf16 v[76:79], v[146:149], v[202:205], v[76:79]
	v_mfma_f32_16x16x32_bf16 v[76:79], v[158:161], v[206:209], v[76:79]
	s_setprio 0
	s_setprio 1
	v_mfma_f32_16x16x32_bf16 v[116:119], v[162:165], v[178:181], v[116:119]
	v_mfma_f32_16x16x32_bf16 v[116:119], v[166:169], v[182:185], v[116:119]
	v_mfma_f32_16x16x32_bf16 v[104:107], v[170:173], v[178:181], v[104:107]
	v_mfma_f32_16x16x32_bf16 v[104:107], v[174:177], v[182:185], v[104:107]
	v_mfma_f32_16x16x32_bf16 v[96:99], v[162:165], v[186:189], v[96:99]
	v_mfma_f32_16x16x32_bf16 v[96:99], v[166:169], v[190:193], v[96:99]
	v_mfma_f32_16x16x32_bf16 v[88:91], v[170:173], v[186:189], v[88:91]
	v_mfma_f32_16x16x32_bf16 v[88:91], v[174:177], v[190:193], v[88:91]
	v_mfma_f32_16x16x32_bf16 v[80:83], v[162:165], v[194:197], v[80:83]
	v_mfma_f32_16x16x32_bf16 v[80:83], v[166:169], v[198:201], v[80:83]
	v_mfma_f32_16x16x32_bf16 v[72:75], v[170:173], v[194:197], v[72:75]
	v_mfma_f32_16x16x32_bf16 v[72:75], v[174:177], v[198:201], v[72:75]
	s_setprio 2
	s_barrier
	v_mfma_f32_16x16x32_bf16 v[68:71], v[162:165], v[202:205], v[68:71]
	ds_read_b128 v[178:181], v155 offset:16384
	ds_read_b128 v[182:185], v155 offset:17408
	v_mfma_f32_16x16x32_bf16 v[68:71], v[166:169], v[206:209], v[68:71]
	ds_read_b128 v[186:189], v155 offset:18432
	ds_read_b128 v[190:193], v155 offset:19456
	v_mfma_f32_16x16x32_bf16 v[64:67], v[170:173], v[202:205], v[64:67]
	ds_read_b128 v[194:197], v155 offset:20480
	ds_read_b128 v[198:201], v155 offset:21504
	v_mfma_f32_16x16x32_bf16 v[64:67], v[174:177], v[206:209], v[64:67]
	s_setprio 0
	s_add_i32 s36, s82, s63
	s_mov_b32 m0, s36
	ds_read_b128 v[202:205], v155 offset:22528
	ds_read_b128 v[206:209], v155 offset:23552
	global_load_lds_dwordx4 v138, vcc
	s_add_i32 m0, s36, 0x2000
	s_add_i32 s36, s83, s63
	s_add_u32 s98, vcc_lo, s0
	s_addc_u32 s99, vcc_hi, s1
	global_load_lds_dwordx4 v138, s[98:99]
	s_mov_b32 m0, s36
	s_nop 0
	s_add_u32 s98, vcc_lo, s6
	s_addc_u32 s99, vcc_hi, s7
	global_load_lds_dwordx4 v138, s[98:99]
	s_add_i32 m0, s36, 0x2000
	s_nop 0
	s_add_u32 s98, vcc_lo, s8
	s_addc_u32 s99, vcc_hi, s9
	global_load_lds_dwordx4 v138, s[98:99]
	s_mov_b32 m0, s33
	s_nop 0
	global_load_lds_dwordx4 v136, s[96:97]
	s_mov_b32 m0, s55
	s_nop 0
	s_add_u32 s98, s96, s0
	s_addc_u32 s99, s97, s1
	global_load_lds_dwordx4 v136, s[98:99]
	s_waitcnt vmcnt(8)
	s_waitcnt lgkmcnt(0)
	s_barrier
	s_setprio 1
	s_waitcnt lgkmcnt(0)
	v_mfma_f32_16x16x32_bf16 v[60:63], v[128:131], v[178:181], v[60:63]
	v_mfma_f32_16x16x32_bf16 v[60:63], v[132:135], v[182:185], v[60:63]
	v_mfma_f32_16x16x32_bf16 v[56:59], v[146:149], v[178:181], v[56:59]
	v_mfma_f32_16x16x32_bf16 v[56:59], v[158:161], v[182:185], v[56:59]
	v_mfma_f32_16x16x32_bf16 v[52:55], v[128:131], v[186:189], v[52:55]
	v_mfma_f32_16x16x32_bf16 v[52:55], v[132:135], v[190:193], v[52:55]
	v_mfma_f32_16x16x32_bf16 v[44:47], v[146:149], v[186:189], v[44:47]
	v_mfma_f32_16x16x32_bf16 v[44:47], v[158:161], v[190:193], v[44:47]
	v_mfma_f32_16x16x32_bf16 v[36:39], v[128:131], v[194:197], v[36:39]
	v_mfma_f32_16x16x32_bf16 v[36:39], v[132:135], v[198:201], v[36:39]
	v_mfma_f32_16x16x32_bf16 v[28:31], v[146:149], v[194:197], v[28:31]
	v_mfma_f32_16x16x32_bf16 v[28:31], v[158:161], v[198:201], v[28:31]
	v_mfma_f32_16x16x32_bf16 v[20:23], v[128:131], v[202:205], v[20:23]
	v_mfma_f32_16x16x32_bf16 v[20:23], v[132:135], v[206:209], v[20:23]
	v_mfma_f32_16x16x32_bf16 v[12:15], v[146:149], v[202:205], v[12:15]
	v_mfma_f32_16x16x32_bf16 v[12:15], v[158:161], v[206:209], v[12:15]
	s_setprio 0
	s_setprio 1
	v_mfma_f32_16x16x32_bf16 v[48:51], v[162:165], v[178:181], v[48:51]
	v_mfma_f32_16x16x32_bf16 v[48:51], v[166:169], v[182:185], v[48:51]
	v_mfma_f32_16x16x32_bf16 v[40:43], v[170:173], v[178:181], v[40:43]
	v_mfma_f32_16x16x32_bf16 v[40:43], v[174:177], v[182:185], v[40:43]
	v_mfma_f32_16x16x32_bf16 v[32:35], v[162:165], v[186:189], v[32:35]
	v_mfma_f32_16x16x32_bf16 v[32:35], v[166:169], v[190:193], v[32:35]
	v_mfma_f32_16x16x32_bf16 v[24:27], v[170:173], v[186:189], v[24:27]
	v_mfma_f32_16x16x32_bf16 v[24:27], v[174:177], v[190:193], v[24:27]
	v_mfma_f32_16x16x32_bf16 v[16:19], v[162:165], v[194:197], v[16:19]
	v_mfma_f32_16x16x32_bf16 v[16:19], v[166:169], v[198:201], v[16:19]
	v_mfma_f32_16x16x32_bf16 v[8:11], v[170:173], v[194:197], v[8:11]
	v_mfma_f32_16x16x32_bf16 v[8:11], v[174:177], v[198:201], v[8:11]
	s_setprio 2
	s_barrier
	v_mfma_f32_16x16x32_bf16 v[4:7], v[162:165], v[202:205], v[4:7]
	ds_read_b128 v[178:181], v155 offset:32768
	ds_read_b128 v[182:185], v155 offset:33792
	v_mfma_f32_16x16x32_bf16 v[4:7], v[166:169], v[206:209], v[4:7]
	ds_read_b128 v[186:189], v155 offset:34816
	ds_read_b128 v[190:193], v155 offset:35840
	v_mfma_f32_16x16x32_bf16 v[0:3], v[170:173], v[202:205], v[0:3]
	ds_read_b128 v[194:197], v155 offset:36864
	ds_read_b128 v[198:201], v155 offset:37888
	v_mfma_f32_16x16x32_bf16 v[0:3], v[174:177], v[206:209], v[0:3]
	s_setprio 0
	s_add_i32 s36, 0, 0x18000
	v_add_u32_e32 v157, s36, v152
	s_add_i32 s37, 0, 0x1c000
	ds_read_b128 v[128:131], v157
	ds_read_b128 v[132:135], v157 offset:1024
	ds_read_b128 v[146:149], v157 offset:2048
	ds_read_b128 v[158:161], v157 offset:3072
	v_add_u32_e32 v157, s37, v152
	ds_read_b128 v[162:165], v157
	ds_read_b128 v[166:169], v157 offset:1024
	ds_read_b128 v[170:173], v157 offset:2048
	ds_read_b128 v[174:177], v157 offset:3072
	s_mov_b32 m0, s57
	ds_read_b128 v[202:205], v155 offset:38912
	ds_read_b128 v[206:209], v155 offset:39936
	s_add_u32 s98, s96, s6
	s_addc_u32 s99, s97, s7
	global_load_lds_dwordx4 v136, s[98:99]
	s_mov_b32 m0, s59
	s_nop 0
	s_add_u32 s98, s96, s8
	s_addc_u32 s99, s97, s9
	global_load_lds_dwordx4 v136, s[98:99]
	s_waitcnt vmcnt(8)
	s_waitcnt lgkmcnt(0)
	s_barrier
	s_setprio 1
	s_waitcnt lgkmcnt(0)
	v_mfma_f32_16x16x32_bf16 v[124:127], v[128:131], v[178:181], v[124:127]
	v_mfma_f32_16x16x32_bf16 v[124:127], v[132:135], v[182:185], v[124:127]
	v_mfma_f32_16x16x32_bf16 v[120:123], v[146:149], v[178:181], v[120:123]
	v_mfma_f32_16x16x32_bf16 v[120:123], v[158:161], v[182:185], v[120:123]
	v_mfma_f32_16x16x32_bf16 v[112:115], v[128:131], v[186:189], v[112:115]
	v_mfma_f32_16x16x32_bf16 v[112:115], v[132:135], v[190:193], v[112:115]
	v_mfma_f32_16x16x32_bf16 v[108:111], v[146:149], v[186:189], v[108:111]
	v_mfma_f32_16x16x32_bf16 v[108:111], v[158:161], v[190:193], v[108:111]
	v_mfma_f32_16x16x32_bf16 v[100:103], v[128:131], v[194:197], v[100:103]
	v_mfma_f32_16x16x32_bf16 v[100:103], v[132:135], v[198:201], v[100:103]
	v_mfma_f32_16x16x32_bf16 v[92:95], v[146:149], v[194:197], v[92:95]
	v_mfma_f32_16x16x32_bf16 v[92:95], v[158:161], v[198:201], v[92:95]
	v_mfma_f32_16x16x32_bf16 v[84:87], v[128:131], v[202:205], v[84:87]
	v_mfma_f32_16x16x32_bf16 v[84:87], v[132:135], v[206:209], v[84:87]
	v_mfma_f32_16x16x32_bf16 v[76:79], v[146:149], v[202:205], v[76:79]
	v_mfma_f32_16x16x32_bf16 v[76:79], v[158:161], v[206:209], v[76:79]
	s_setprio 0
	s_setprio 1
	v_mfma_f32_16x16x32_bf16 v[116:119], v[162:165], v[178:181], v[116:119]
	v_mfma_f32_16x16x32_bf16 v[116:119], v[166:169], v[182:185], v[116:119]
	v_mfma_f32_16x16x32_bf16 v[104:107], v[170:173], v[178:181], v[104:107]
	v_mfma_f32_16x16x32_bf16 v[104:107], v[174:177], v[182:185], v[104:107]
	v_mfma_f32_16x16x32_bf16 v[96:99], v[162:165], v[186:189], v[96:99]
	v_mfma_f32_16x16x32_bf16 v[96:99], v[166:169], v[190:193], v[96:99]
	v_mfma_f32_16x16x32_bf16 v[88:91], v[170:173], v[186:189], v[88:91]
	v_mfma_f32_16x16x32_bf16 v[88:91], v[174:177], v[190:193], v[88:91]
	v_mfma_f32_16x16x32_bf16 v[80:83], v[162:165], v[194:197], v[80:83]
	v_mfma_f32_16x16x32_bf16 v[80:83], v[166:169], v[198:201], v[80:83]
	v_mfma_f32_16x16x32_bf16 v[72:75], v[170:173], v[194:197], v[72:75]
	v_mfma_f32_16x16x32_bf16 v[72:75], v[174:177], v[198:201], v[72:75]
	s_setprio 2
	s_barrier
	v_mfma_f32_16x16x32_bf16 v[68:71], v[162:165], v[202:205], v[68:71]
	ds_read_b128 v[178:181], v155 offset:49152
	ds_read_b128 v[182:185], v155 offset:50176
	v_mfma_f32_16x16x32_bf16 v[68:71], v[166:169], v[206:209], v[68:71]
	ds_read_b128 v[186:189], v155 offset:51200
	ds_read_b128 v[190:193], v155 offset:52224
	v_mfma_f32_16x16x32_bf16 v[64:67], v[170:173], v[202:205], v[64:67]
	ds_read_b128 v[194:197], v155 offset:53248
	ds_read_b128 v[198:201], v155 offset:54272
	v_mfma_f32_16x16x32_bf16 v[64:67], v[174:177], v[206:209], v[64:67]
	s_setprio 0
	s_add_i32 s36, s36, s63
	s_mov_b32 m0, s36
	ds_read_b128 v[202:205], v155 offset:55296
	ds_read_b128 v[206:209], v155 offset:56320
	s_add_u32 s98, vcc_lo, s24
	s_addc_u32 s99, vcc_hi, s25
	global_load_lds_dwordx4 v138, s[98:99]
	s_add_i32 m0, s36, 0x2000
	s_add_i32 s36, s37, s63
	s_add_u32 s98, vcc_lo, s34
	s_addc_u32 s99, vcc_hi, s35
	global_load_lds_dwordx4 v138, s[98:99]
	s_mov_b32 m0, s36
	s_add_u32 s98, vcc_lo, s12
	s_addc_u32 s99, vcc_hi, s13
	global_load_lds_dwordx4 v138, s[98:99]
	s_add_i32 m0, s36, 0x2000
	s_nop 0
	s_add_u32 s98, vcc_lo, s18
	s_addc_u32 s99, vcc_hi, s19
	global_load_lds_dwordx4 v138, s[98:99]
	s_mov_b32 m0, s68
	s_nop 0
	s_add_u32 s98, s96, s24
	s_addc_u32 s99, s97, s25
	global_load_lds_dwordx4 v136, s[98:99]
	s_mov_b32 m0, s69
	s_nop 0
	s_add_u32 s98, s96, s34
	s_addc_u32 s99, s97, s35
	global_load_lds_dwordx4 v136, s[98:99]
	s_waitcnt vmcnt(8)
	s_waitcnt lgkmcnt(0)
	s_barrier
	s_setprio 1
	s_waitcnt lgkmcnt(0)
	v_mfma_f32_16x16x32_bf16 v[60:63], v[128:131], v[178:181], v[60:63]
	v_mfma_f32_16x16x32_bf16 v[60:63], v[132:135], v[182:185], v[60:63]
	v_mfma_f32_16x16x32_bf16 v[56:59], v[146:149], v[178:181], v[56:59]
	v_mfma_f32_16x16x32_bf16 v[56:59], v[158:161], v[182:185], v[56:59]
	v_mfma_f32_16x16x32_bf16 v[52:55], v[128:131], v[186:189], v[52:55]
	v_mfma_f32_16x16x32_bf16 v[52:55], v[132:135], v[190:193], v[52:55]
	v_mfma_f32_16x16x32_bf16 v[44:47], v[146:149], v[186:189], v[44:47]
	v_mfma_f32_16x16x32_bf16 v[44:47], v[158:161], v[190:193], v[44:47]
	v_mfma_f32_16x16x32_bf16 v[36:39], v[128:131], v[194:197], v[36:39]
	v_mfma_f32_16x16x32_bf16 v[36:39], v[132:135], v[198:201], v[36:39]
	v_mfma_f32_16x16x32_bf16 v[28:31], v[146:149], v[194:197], v[28:31]
	v_mfma_f32_16x16x32_bf16 v[28:31], v[158:161], v[198:201], v[28:31]
	v_mfma_f32_16x16x32_bf16 v[20:23], v[128:131], v[202:205], v[20:23]
	v_mfma_f32_16x16x32_bf16 v[20:23], v[132:135], v[206:209], v[20:23]
	v_mfma_f32_16x16x32_bf16 v[12:15], v[146:149], v[202:205], v[12:15]
	v_mfma_f32_16x16x32_bf16 v[12:15], v[158:161], v[206:209], v[12:15]
	s_setprio 0
	s_setprio 1
	v_mfma_f32_16x16x32_bf16 v[48:51], v[162:165], v[178:181], v[48:51]
	v_mfma_f32_16x16x32_bf16 v[48:51], v[166:169], v[182:185], v[48:51]
	v_mfma_f32_16x16x32_bf16 v[40:43], v[170:173], v[178:181], v[40:43]
	v_mfma_f32_16x16x32_bf16 v[40:43], v[174:177], v[182:185], v[40:43]
	v_mfma_f32_16x16x32_bf16 v[32:35], v[162:165], v[186:189], v[32:35]
	v_mfma_f32_16x16x32_bf16 v[32:35], v[166:169], v[190:193], v[32:35]
	v_mfma_f32_16x16x32_bf16 v[24:27], v[170:173], v[186:189], v[24:27]
	v_mfma_f32_16x16x32_bf16 v[24:27], v[174:177], v[190:193], v[24:27]
	v_mfma_f32_16x16x32_bf16 v[16:19], v[162:165], v[194:197], v[16:19]
	v_mfma_f32_16x16x32_bf16 v[16:19], v[166:169], v[198:201], v[16:19]
	v_mfma_f32_16x16x32_bf16 v[8:11], v[170:173], v[194:197], v[8:11]
	v_mfma_f32_16x16x32_bf16 v[8:11], v[174:177], v[198:201], v[8:11]
	s_setprio 2
	s_barrier
	v_mfma_f32_16x16x32_bf16 v[4:7], v[162:165], v[202:205], v[4:7]
	v_mfma_f32_16x16x32_bf16 v[4:7], v[166:169], v[206:209], v[4:7]
	v_mfma_f32_16x16x32_bf16 v[0:3], v[170:173], v[202:205], v[0:3]
	v_mfma_f32_16x16x32_bf16 v[0:3], v[174:177], v[206:209], v[0:3]
	s_setprio 0
	s_add_i32 s81, s81, 2
	s_add_u32 s22, s22, 0x100
	s_addc_u32 s80, s80, 0
	s_add_u32 s78, s78, 0x100
	s_addc_u32 s79, s79, 0
	s_cmp_gt_u32 s81, 61
	s_cbranch_scc0 .LBB0_298
	s_and_b64 vcc, exec, s[26:27]
	s_cbranch_vccz .LBB0_301
	s_barrier

.LBB0_627:
	ds_read_b128 v[128:131], v151
	ds_read_b128 v[142:145], v151 offset:1024
	ds_read_b128 v[146:149], v151 offset:2048
	ds_read_b128 v[154:157], v151 offset:3072
	ds_read_b128 v[158:161], v152
	ds_read_b128 v[162:165], v152 offset:1024
	ds_read_b128 v[166:169], v152 offset:2048
	ds_read_b128 v[170:173], v152 offset:3072
	s_add_u32 s50, s60, 0xfff00080
	s_addc_u32 s51, s61, -1
	s_cmp_eq_u32 s62, 60
	s_cselect_b32 s77, s5, s51
	s_cselect_b32 s76, s49, s50
	s_cselect_b32 s79, s47, s75
	s_cselect_b32 s78, s59, s74
	s_add_i32 m0, s20, 0xc000
	ds_read_b128 v[174:177], v153
	ds_read_b128 v[178:181], v153 offset:1024
	ds_read_b128 v[182:185], v153 offset:2048
	ds_read_b128 v[186:189], v153 offset:3072
	ds_read_b128 v[190:193], v153 offset:4096
	ds_read_b128 v[194:197], v153 offset:5120
	ds_read_b128 v[198:201], v153 offset:6144
	ds_read_b128 v[202:205], v153 offset:7168
	global_load_lds_dwordx4 v136, s[60:61]
	s_add_i32 m0, s20, 0xe000
	s_nop 0
	s_add_u32 s98, s60, s6
	s_addc_u32 s99, s61, s7
	global_load_lds_dwordx4 v136, s[98:99]
	s_waitcnt vmcnt(8)
	s_waitcnt lgkmcnt(0)
	s_barrier
	s_setprio 1
	s_waitcnt lgkmcnt(0)
	v_mfma_f32_16x16x32_bf16 v[124:127], v[128:131], v[174:177], v[124:127]
	v_mfma_f32_16x16x32_bf16 v[124:127], v[142:145], v[178:181], v[124:127]
	v_mfma_f32_16x16x32_bf16 v[120:123], v[146:149], v[174:177], v[120:123]
	v_mfma_f32_16x16x32_bf16 v[120:123], v[154:157], v[178:181], v[120:123]
	v_mfma_f32_16x16x32_bf16 v[116:119], v[128:131], v[182:185], v[116:119]
	v_mfma_f32_16x16x32_bf16 v[116:119], v[142:145], v[186:189], v[116:119]
	v_mfma_f32_16x16x32_bf16 v[112:115], v[146:149], v[182:185], v[112:115]
	v_mfma_f32_16x16x32_bf16 v[112:115], v[154:157], v[186:189], v[112:115]
	v_mfma_f32_16x16x32_bf16 v[108:111], v[128:131], v[190:193], v[108:111]
	v_mfma_f32_16x16x32_bf16 v[108:111], v[142:145], v[194:197], v[108:111]
	v_mfma_f32_16x16x32_bf16 v[104:107], v[146:149], v[190:193], v[104:107]
	v_mfma_f32_16x16x32_bf16 v[104:107], v[154:157], v[194:197], v[104:107]
	v_mfma_f32_16x16x32_bf16 v[100:103], v[128:131], v[198:201], v[100:103]
	v_mfma_f32_16x16x32_bf16 v[100:103], v[142:145], v[202:205], v[100:103]
	v_mfma_f32_16x16x32_bf16 v[96:99], v[146:149], v[198:201], v[96:99]
	v_mfma_f32_16x16x32_bf16 v[96:99], v[154:157], v[202:205], v[96:99]
	s_setprio 0
	s_setprio 1
	v_mfma_f32_16x16x32_bf16 v[92:95], v[158:161], v[174:177], v[92:95]
	v_mfma_f32_16x16x32_bf16 v[92:95], v[162:165], v[178:181], v[92:95]
	v_mfma_f32_16x16x32_bf16 v[88:91], v[166:169], v[174:177], v[88:91]
	v_mfma_f32_16x16x32_bf16 v[88:91], v[170:173], v[178:181], v[88:91]
	v_mfma_f32_16x16x32_bf16 v[84:87], v[158:161], v[182:185], v[84:87]
	v_mfma_f32_16x16x32_bf16 v[84:87], v[162:165], v[186:189], v[84:87]
	v_mfma_f32_16x16x32_bf16 v[80:83], v[166:169], v[182:185], v[80:83]
	v_mfma_f32_16x16x32_bf16 v[80:83], v[170:173], v[186:189], v[80:83]
	v_mfma_f32_16x16x32_bf16 v[76:79], v[158:161], v[190:193], v[76:79]
	v_mfma_f32_16x16x32_bf16 v[76:79], v[162:165], v[194:197], v[76:79]
	v_mfma_f32_16x16x32_bf16 v[72:75], v[166:169], v[190:193], v[72:75]
	v_mfma_f32_16x16x32_bf16 v[72:75], v[170:173], v[194:197], v[72:75]
	s_setprio 2
	s_barrier
	v_mfma_f32_16x16x32_bf16 v[68:71], v[158:161], v[198:201], v[68:71]
	ds_read_b128 v[174:177], v153 offset:16384
	ds_read_b128 v[178:181], v153 offset:17408
	v_mfma_f32_16x16x32_bf16 v[68:71], v[162:165], v[202:205], v[68:71]
	ds_read_b128 v[182:185], v153 offset:18432
	ds_read_b128 v[186:189], v153 offset:19456
	v_mfma_f32_16x16x32_bf16 v[64:67], v[166:169], v[198:201], v[64:67]
	ds_read_b128 v[190:193], v153 offset:20480
	ds_read_b128 v[194:197], v153 offset:21504
	v_mfma_f32_16x16x32_bf16 v[64:67], v[170:173], v[202:205], v[64:67]
	s_setprio 0
	s_add_i32 s50, s72, s14
	s_mov_b32 m0, s50
	ds_read_b128 v[198:201], v153 offset:22528
	ds_read_b128 v[202:205], v153 offset:23552
	global_load_lds_dwordx4 v134, s[78:79]
	s_add_i32 m0, s50, 0x2000
	s_add_i32 s50, s73, s14
	s_add_u32 s98, s78, s6
	s_addc_u32 s99, s79, s7
	global_load_lds_dwordx4 v134, s[98:99]
	s_mov_b32 m0, s50
	s_nop 0
	s_add_u32 s98, s78, s8
	s_addc_u32 s99, s79, s9
	global_load_lds_dwordx4 v134, s[98:99]
	s_add_i32 m0, s50, 0x2000
	s_nop 0
	s_add_u32 s98, s78, s10
	s_addc_u32 s99, s79, s11
	global_load_lds_dwordx4 v134, s[98:99]
	s_mov_b32 m0, s20
	s_nop 0
	global_load_lds_dwordx4 v132, s[76:77]
	s_mov_b32 m0, s21
	s_nop 0
	s_add_u32 s98, s76, s6
	s_addc_u32 s99, s77, s7
	global_load_lds_dwordx4 v132, s[98:99]
	s_waitcnt vmcnt(8)
	s_waitcnt lgkmcnt(0)
	s_barrier
	s_setprio 1
	s_waitcnt lgkmcnt(0)
	v_mfma_f32_16x16x32_bf16 v[60:63], v[128:131], v[174:177], v[60:63]
	v_mfma_f32_16x16x32_bf16 v[60:63], v[142:145], v[178:181], v[60:63]
	v_mfma_f32_16x16x32_bf16 v[56:59], v[146:149], v[174:177], v[56:59]
	v_mfma_f32_16x16x32_bf16 v[56:59], v[154:157], v[178:181], v[56:59]
	v_mfma_f32_16x16x32_bf16 v[52:55], v[128:131], v[182:185], v[52:55]
	v_mfma_f32_16x16x32_bf16 v[52:55], v[142:145], v[186:189], v[52:55]
	v_mfma_f32_16x16x32_bf16 v[48:51], v[146:149], v[182:185], v[48:51]
	v_mfma_f32_16x16x32_bf16 v[48:51], v[154:157], v[186:189], v[48:51]
	v_mfma_f32_16x16x32_bf16 v[44:47], v[128:131], v[190:193], v[44:47]
	v_mfma_f32_16x16x32_bf16 v[44:47], v[142:145], v[194:197], v[44:47]
	v_mfma_f32_16x16x32_bf16 v[40:43], v[146:149], v[190:193], v[40:43]
	v_mfma_f32_16x16x32_bf16 v[40:43], v[154:157], v[194:197], v[40:43]
	v_mfma_f32_16x16x32_bf16 v[36:39], v[128:131], v[198:201], v[36:39]
	v_mfma_f32_16x16x32_bf16 v[36:39], v[142:145], v[202:205], v[36:39]
	v_mfma_f32_16x16x32_bf16 v[32:35], v[146:149], v[198:201], v[32:35]
	v_mfma_f32_16x16x32_bf16 v[32:35], v[154:157], v[202:205], v[32:35]
	s_setprio 0
	s_setprio 1
	v_mfma_f32_16x16x32_bf16 v[28:31], v[158:161], v[174:177], v[28:31]
	v_mfma_f32_16x16x32_bf16 v[28:31], v[162:165], v[178:181], v[28:31]
	v_mfma_f32_16x16x32_bf16 v[24:27], v[166:169], v[174:177], v[24:27]
	v_mfma_f32_16x16x32_bf16 v[24:27], v[170:173], v[178:181], v[24:27]
	v_mfma_f32_16x16x32_bf16 v[20:23], v[158:161], v[182:185], v[20:23]
	v_mfma_f32_16x16x32_bf16 v[20:23], v[162:165], v[186:189], v[20:23]
	v_mfma_f32_16x16x32_bf16 v[16:19], v[166:169], v[182:185], v[16:19]
	v_mfma_f32_16x16x32_bf16 v[16:19], v[170:173], v[186:189], v[16:19]
	v_mfma_f32_16x16x32_bf16 v[12:15], v[158:161], v[190:193], v[12:15]
	v_mfma_f32_16x16x32_bf16 v[12:15], v[162:165], v[194:197], v[12:15]
	v_mfma_f32_16x16x32_bf16 v[8:11], v[166:169], v[190:193], v[8:11]
	v_mfma_f32_16x16x32_bf16 v[8:11], v[170:173], v[194:197], v[8:11]
	s_setprio 2
	s_barrier
	v_mfma_f32_16x16x32_bf16 v[4:7], v[158:161], v[198:201], v[4:7]
	ds_read_b128 v[174:177], v153 offset:32768
	ds_read_b128 v[178:181], v153 offset:33792
	v_mfma_f32_16x16x32_bf16 v[4:7], v[162:165], v[202:205], v[4:7]
	ds_read_b128 v[182:185], v153 offset:34816
	ds_read_b128 v[186:189], v153 offset:35840
	v_mfma_f32_16x16x32_bf16 v[0:3], v[166:169], v[198:201], v[0:3]
	ds_read_b128 v[190:193], v153 offset:36864
	ds_read_b128 v[194:197], v153 offset:37888
	v_mfma_f32_16x16x32_bf16 v[0:3], v[170:173], v[202:205], v[0:3]
	s_setprio 0
	s_add_i32 s50, 0, 0x18000
	s_add_i32 s51, 0, 0x1c000
	v_add_u32_e32 v154, s50, v150
	v_add_u32_e32 v170, s51, v150
	ds_read_b128 v[128:131], v154
	ds_read_b128 v[142:145], v154 offset:1024
	ds_read_b128 v[146:149], v154 offset:2048
	ds_read_b128 v[154:157], v154 offset:3072
	ds_read_b128 v[158:161], v170
	ds_read_b128 v[162:165], v170 offset:1024
	ds_read_b128 v[166:169], v170 offset:2048
	ds_read_b128 v[170:173], v170 offset:3072
	s_mov_b32 m0, s33
	ds_read_b128 v[198:201], v153 offset:38912
	ds_read_b128 v[202:205], v153 offset:39936
	s_add_u32 s98, s76, s8
	s_addc_u32 s99, s77, s9
	global_load_lds_dwordx4 v132, s[98:99]
	s_mov_b32 m0, s64
	s_nop 0
	s_add_u32 s98, s76, s10
	s_addc_u32 s99, s77, s11
	global_load_lds_dwordx4 v132, s[98:99]
	s_waitcnt vmcnt(8)
	s_waitcnt lgkmcnt(0)
	s_barrier
	s_setprio 1
	s_waitcnt lgkmcnt(0)
	v_mfma_f32_16x16x32_bf16 v[124:127], v[128:131], v[174:177], v[124:127]
	v_mfma_f32_16x16x32_bf16 v[124:127], v[142:145], v[178:181], v[124:127]
	v_mfma_f32_16x16x32_bf16 v[120:123], v[146:149], v[174:177], v[120:123]
	v_mfma_f32_16x16x32_bf16 v[120:123], v[154:157], v[178:181], v[120:123]
	v_mfma_f32_16x16x32_bf16 v[116:119], v[128:131], v[182:185], v[116:119]
	v_mfma_f32_16x16x32_bf16 v[116:119], v[142:145], v[186:189], v[116:119]
	v_mfma_f32_16x16x32_bf16 v[112:115], v[146:149], v[182:185], v[112:115]
	v_mfma_f32_16x16x32_bf16 v[112:115], v[154:157], v[186:189], v[112:115]
	v_mfma_f32_16x16x32_bf16 v[108:111], v[128:131], v[190:193], v[108:111]
	v_mfma_f32_16x16x32_bf16 v[108:111], v[142:145], v[194:197], v[108:111]
	v_mfma_f32_16x16x32_bf16 v[104:107], v[146:149], v[190:193], v[104:107]
	v_mfma_f32_16x16x32_bf16 v[104:107], v[154:157], v[194:197], v[104:107]
	v_mfma_f32_16x16x32_bf16 v[100:103], v[128:131], v[198:201], v[100:103]
	v_mfma_f32_16x16x32_bf16 v[100:103], v[142:145], v[202:205], v[100:103]
	v_mfma_f32_16x16x32_bf16 v[96:99], v[146:149], v[198:201], v[96:99]
	v_mfma_f32_16x16x32_bf16 v[96:99], v[154:157], v[202:205], v[96:99]
	s_setprio 0
	s_setprio 1
	v_mfma_f32_16x16x32_bf16 v[92:95], v[158:161], v[174:177], v[92:95]
	v_mfma_f32_16x16x32_bf16 v[92:95], v[162:165], v[178:181], v[92:95]
	v_mfma_f32_16x16x32_bf16 v[88:91], v[166:169], v[174:177], v[88:91]
	v_mfma_f32_16x16x32_bf16 v[88:91], v[170:173], v[178:181], v[88:91]
	v_mfma_f32_16x16x32_bf16 v[84:87], v[158:161], v[182:185], v[84:87]
	v_mfma_f32_16x16x32_bf16 v[84:87], v[162:165], v[186:189], v[84:87]
	v_mfma_f32_16x16x32_bf16 v[80:83], v[166:169], v[182:185], v[80:83]
	v_mfma_f32_16x16x32_bf16 v[80:83], v[170:173], v[186:189], v[80:83]
	v_mfma_f32_16x16x32_bf16 v[76:79], v[158:161], v[190:193], v[76:79]
	v_mfma_f32_16x16x32_bf16 v[76:79], v[162:165], v[194:197], v[76:79]
	v_mfma_f32_16x16x32_bf16 v[72:75], v[166:169], v[190:193], v[72:75]
	v_mfma_f32_16x16x32_bf16 v[72:75], v[170:173], v[194:197], v[72:75]
	s_setprio 2
	s_barrier
	v_mfma_f32_16x16x32_bf16 v[68:71], v[158:161], v[198:201], v[68:71]
	ds_read_b128 v[174:177], v153 offset:49152
	ds_read_b128 v[178:181], v153 offset:50176
	v_mfma_f32_16x16x32_bf16 v[68:71], v[162:165], v[202:205], v[68:71]
	ds_read_b128 v[182:185], v153 offset:51200
	ds_read_b128 v[186:189], v153 offset:52224
	v_mfma_f32_16x16x32_bf16 v[64:67], v[166:169], v[198:201], v[64:67]
	ds_read_b128 v[190:193], v153 offset:53248
	ds_read_b128 v[194:197], v153 offset:54272
	v_mfma_f32_16x16x32_bf16 v[64:67], v[170:173], v[202:205], v[64:67]
	s_setprio 0
	s_add_i32 s50, s50, s14
	s_mov_b32 m0, s50
	ds_read_b128 v[198:201], v153 offset:55296
	ds_read_b128 v[202:205], v153 offset:56320
	s_add_u32 s98, s78, s24
	s_addc_u32 s99, s79, s25
	global_load_lds_dwordx4 v134, s[98:99]
	s_add_i32 m0, s50, 0x2000
	s_add_i32 s50, s51, s14
	s_add_u32 s98, s78, s34
	s_addc_u32 s99, s79, s35
	global_load_lds_dwordx4 v134, s[98:99]
	s_mov_b32 m0, s50
	s_add_u32 s98, s78, s36
	s_addc_u32 s99, s79, s37
	global_load_lds_dwordx4 v134, s[98:99]
	s_add_i32 m0, s50, 0x2000
	s_nop 0
	s_add_u32 s98, s78, s38
	s_addc_u32 s99, s79, s39
	global_load_lds_dwordx4 v134, s[98:99]
	s_mov_b32 m0, s66
	s_nop 0
	s_add_u32 s98, s76, s24
	s_addc_u32 s99, s77, s25
	global_load_lds_dwordx4 v132, s[98:99]
	s_mov_b32 m0, s67
	s_nop 0
	s_add_u32 s98, s76, s34
	s_addc_u32 s99, s77, s35
	global_load_lds_dwordx4 v132, s[98:99]
	s_waitcnt vmcnt(8)
	s_waitcnt lgkmcnt(0)
	s_barrier
	s_setprio 1
	s_waitcnt lgkmcnt(0)
	v_mfma_f32_16x16x32_bf16 v[60:63], v[128:131], v[174:177], v[60:63]
	v_mfma_f32_16x16x32_bf16 v[60:63], v[142:145], v[178:181], v[60:63]
	v_mfma_f32_16x16x32_bf16 v[56:59], v[146:149], v[174:177], v[56:59]
	v_mfma_f32_16x16x32_bf16 v[56:59], v[154:157], v[178:181], v[56:59]
	v_mfma_f32_16x16x32_bf16 v[52:55], v[128:131], v[182:185], v[52:55]
	v_mfma_f32_16x16x32_bf16 v[52:55], v[142:145], v[186:189], v[52:55]
	v_mfma_f32_16x16x32_bf16 v[48:51], v[146:149], v[182:185], v[48:51]
	v_mfma_f32_16x16x32_bf16 v[48:51], v[154:157], v[186:189], v[48:51]
	v_mfma_f32_16x16x32_bf16 v[44:47], v[128:131], v[190:193], v[44:47]
	v_mfma_f32_16x16x32_bf16 v[44:47], v[142:145], v[194:197], v[44:47]
	v_mfma_f32_16x16x32_bf16 v[40:43], v[146:149], v[190:193], v[40:43]
	v_mfma_f32_16x16x32_bf16 v[40:43], v[154:157], v[194:197], v[40:43]
	v_mfma_f32_16x16x32_bf16 v[36:39], v[128:131], v[198:201], v[36:39]
	v_mfma_f32_16x16x32_bf16 v[36:39], v[142:145], v[202:205], v[36:39]
	v_mfma_f32_16x16x32_bf16 v[32:35], v[146:149], v[198:201], v[32:35]
	v_mfma_f32_16x16x32_bf16 v[32:35], v[154:157], v[202:205], v[32:35]
	s_setprio 0
	s_setprio 1
	v_mfma_f32_16x16x32_bf16 v[28:31], v[158:161], v[174:177], v[28:31]
	v_mfma_f32_16x16x32_bf16 v[28:31], v[162:165], v[178:181], v[28:31]
	v_mfma_f32_16x16x32_bf16 v[24:27], v[166:169], v[174:177], v[24:27]
	v_mfma_f32_16x16x32_bf16 v[24:27], v[170:173], v[178:181], v[24:27]
	v_mfma_f32_16x16x32_bf16 v[20:23], v[158:161], v[182:185], v[20:23]
	v_mfma_f32_16x16x32_bf16 v[20:23], v[162:165], v[186:189], v[20:23]
	v_mfma_f32_16x16x32_bf16 v[16:19], v[166:169], v[182:185], v[16:19]
	v_mfma_f32_16x16x32_bf16 v[16:19], v[170:173], v[186:189], v[16:19]
	v_mfma_f32_16x16x32_bf16 v[12:15], v[158:161], v[190:193], v[12:15]
	v_mfma_f32_16x16x32_bf16 v[12:15], v[162:165], v[194:197], v[12:15]
	v_mfma_f32_16x16x32_bf16 v[8:11], v[166:169], v[190:193], v[8:11]
	v_mfma_f32_16x16x32_bf16 v[8:11], v[170:173], v[194:197], v[8:11]
	s_setprio 2
	s_barrier
	v_mfma_f32_16x16x32_bf16 v[4:7], v[158:161], v[198:201], v[4:7]
	v_mfma_f32_16x16x32_bf16 v[4:7], v[162:165], v[202:205], v[4:7]
	v_mfma_f32_16x16x32_bf16 v[0:3], v[166:169], v[198:201], v[0:3]
	v_mfma_f32_16x16x32_bf16 v[0:3], v[170:173], v[202:205], v[0:3]
	s_setprio 0
	s_add_i32 s62, s62, 2
	s_add_u32 s74, s74, 0x100
	s_addc_u32 s75, s75, 0
	s_add_u32 s60, s60, 0x100
	s_addc_u32 s61, s61, 0
	s_cmp_gt_u32 s62, 61
	s_cbranch_scc0 .LBB0_627
	s_and_b64 vcc, exec, s[40:41]
	s_cbranch_vccz .LBB0_630
	s_barrier

.LBB0_800:
	ds_read_b128 v[128:131], v187
	ds_read_b128 v[132:135], v187 offset:1024
	ds_read_b128 v[136:139], v187 offset:2048
	ds_read_b128 v[140:143], v187 offset:3072
	ds_read_b128 v[144:147], v188
	ds_read_b128 v[148:151], v188 offset:1024
	ds_read_b128 v[152:155], v188 offset:2048
	ds_read_b128 v[156:159], v188 offset:3072
	s_add_u32 s9, s6, 0xfff80080
	s_addc_u32 s50, s7, -1
	s_cmp_eq_u32 s8, 28
	s_cselect_b32 vcc_hi, s5, s50
	s_cselect_b32 vcc_lo, s10, s9
	s_cselect_b32 s51, s11, s78
	s_cselect_b32 s50, s73, s75
	s_add_i32 m0, s65, 0xc000
	ds_read_b128 v[160:163], v189
	ds_read_b128 v[164:167], v189 offset:1024
	ds_read_b128 v[168:171], v189 offset:2048
	ds_read_b128 v[192:195], v189 offset:3072
	ds_read_b128 v[196:199], v189 offset:4096
	ds_read_b128 v[200:203], v189 offset:5120
	ds_read_b128 v[204:207], v189 offset:6144
	ds_read_b128 v[208:211], v189 offset:7168
	global_load_lds_dwordx4 v178, s[6:7]
	s_add_i32 m0, s65, 0xe000
	s_nop 0
	s_add_u32 s98, s6, s36
	s_addc_u32 s99, s7, s37
	global_load_lds_dwordx4 v178, s[98:99]
	s_waitcnt vmcnt(8)
	s_waitcnt lgkmcnt(0)
	s_barrier
	s_setprio 1
	s_waitcnt lgkmcnt(0)
	v_mfma_i32_16x16x64_i8 v[84:87], v[128:131], v[160:163], v[84:87]
	v_mfma_i32_16x16x64_i8 v[84:87], v[132:135], v[164:167], v[84:87]
	v_mfma_i32_16x16x64_i8 v[16:19], v[136:139], v[160:163], v[16:19]
	v_mfma_i32_16x16x64_i8 v[16:19], v[140:143], v[164:167], v[16:19]
	v_mfma_i32_16x16x64_i8 v[88:91], v[128:131], v[168:171], v[88:91]
	v_mfma_i32_16x16x64_i8 v[88:91], v[132:135], v[192:195], v[88:91]
	v_mfma_i32_16x16x64_i8 v[20:23], v[136:139], v[168:171], v[20:23]
	v_mfma_i32_16x16x64_i8 v[20:23], v[140:143], v[192:195], v[20:23]
	v_mfma_i32_16x16x64_i8 v[92:95], v[128:131], v[196:199], v[92:95]
	v_mfma_i32_16x16x64_i8 v[92:95], v[132:135], v[200:203], v[92:95]
	v_mfma_i32_16x16x64_i8 v[24:27], v[136:139], v[196:199], v[24:27]
	v_mfma_i32_16x16x64_i8 v[24:27], v[140:143], v[200:203], v[24:27]
	v_mfma_i32_16x16x64_i8 v[96:99], v[128:131], v[204:207], v[96:99]
	v_mfma_i32_16x16x64_i8 v[96:99], v[132:135], v[208:211], v[96:99]
	v_mfma_i32_16x16x64_i8 v[28:31], v[136:139], v[204:207], v[28:31]
	v_mfma_i32_16x16x64_i8 v[28:31], v[140:143], v[208:211], v[28:31]
	s_setprio 0
	s_setprio 1
	v_mfma_i32_16x16x64_i8 v[124:127], v[144:147], v[160:163], v[124:127]
	v_mfma_i32_16x16x64_i8 v[124:127], v[148:151], v[164:167], v[124:127]
	v_mfma_i32_16x16x64_i8 v[68:71], v[152:155], v[160:163], v[68:71]
	v_mfma_i32_16x16x64_i8 v[68:71], v[156:159], v[164:167], v[68:71]
	v_mfma_i32_16x16x64_i8 v[120:123], v[144:147], v[168:171], v[120:123]
	v_mfma_i32_16x16x64_i8 v[120:123], v[148:151], v[192:195], v[120:123]
	v_mfma_i32_16x16x64_i8 v[72:75], v[152:155], v[168:171], v[72:75]
	v_mfma_i32_16x16x64_i8 v[72:75], v[156:159], v[192:195], v[72:75]
	v_mfma_i32_16x16x64_i8 v[116:119], v[144:147], v[196:199], v[116:119]
	v_mfma_i32_16x16x64_i8 v[116:119], v[148:151], v[200:203], v[116:119]
	v_mfma_i32_16x16x64_i8 v[80:83], v[152:155], v[196:199], v[80:83]
	v_mfma_i32_16x16x64_i8 v[80:83], v[156:159], v[200:203], v[80:83]
	s_setprio 2
	s_barrier
	v_mfma_i32_16x16x64_i8 v[112:115], v[144:147], v[204:207], v[112:115]
	ds_read_b128 v[160:163], v189 offset:16384
	ds_read_b128 v[164:167], v189 offset:17408
	v_mfma_i32_16x16x64_i8 v[112:115], v[148:151], v[208:211], v[112:115]
	ds_read_b128 v[168:171], v189 offset:18432
	ds_read_b128 v[192:195], v189 offset:19456
	v_mfma_i32_16x16x64_i8 v[60:63], v[152:155], v[204:207], v[60:63]
	ds_read_b128 v[196:199], v189 offset:20480
	ds_read_b128 v[200:203], v189 offset:21504
	v_mfma_i32_16x16x64_i8 v[60:63], v[156:159], v[208:211], v[60:63]
	s_setprio 0
	s_add_i32 s9, s80, s33
	s_mov_b64 s[100:101], s[50:51]
	s_mov_b32 m0, s9
	ds_read_b128 v[204:207], v189 offset:22528
	ds_read_b128 v[208:211], v189 offset:23552
	global_load_lds_dwordx4 v174, s[50:51]
	s_add_i32 m0, s9, 0x2000
	s_add_i32 s9, s81, s33
	s_add_u32 s98, s50, s36
	s_addc_u32 s99, s51, s37
	global_load_lds_dwordx4 v174, s[98:99]
	s_mov_b32 m0, s9
	s_nop 0
	s_add_u32 s98, s50, s38
	s_addc_u32 s99, s51, s39
	global_load_lds_dwordx4 v174, s[98:99]
	s_add_i32 m0, s9, 0x2000
	s_nop 0
	s_add_u32 s98, s50, s40
	s_addc_u32 s99, s51, s41
	global_load_lds_dwordx4 v174, s[98:99]
	s_mov_b32 m0, s65
	s_nop 0
	global_load_lds_dwordx4 v172, vcc
	s_mov_b32 m0, s67
	s_nop 0
	s_add_u32 s98, vcc_lo, s36
	s_addc_u32 s99, vcc_hi, s37
	global_load_lds_dwordx4 v172, s[98:99]
	s_waitcnt vmcnt(8)
	s_waitcnt lgkmcnt(0)
	s_barrier
	s_setprio 1
	s_waitcnt lgkmcnt(0)
	v_mfma_i32_16x16x64_i8 v[48:51], v[128:131], v[160:163], v[48:51]
	v_mfma_i32_16x16x64_i8 v[48:51], v[132:135], v[164:167], v[48:51]
	v_mfma_i32_16x16x64_i8 v[0:3], v[136:139], v[160:163], v[0:3]
	v_mfma_i32_16x16x64_i8 v[0:3], v[140:143], v[164:167], v[0:3]
	v_mfma_i32_16x16x64_i8 v[52:55], v[128:131], v[168:171], v[52:55]
	v_mfma_i32_16x16x64_i8 v[52:55], v[132:135], v[192:195], v[52:55]
	v_mfma_i32_16x16x64_i8 v[4:7], v[136:139], v[168:171], v[4:7]
	v_mfma_i32_16x16x64_i8 v[4:7], v[140:143], v[192:195], v[4:7]
	v_mfma_i32_16x16x64_i8 v[56:59], v[128:131], v[196:199], v[56:59]
	v_mfma_i32_16x16x64_i8 v[56:59], v[132:135], v[200:203], v[56:59]
	v_mfma_i32_16x16x64_i8 v[8:11], v[136:139], v[196:199], v[8:11]
	v_mfma_i32_16x16x64_i8 v[8:11], v[140:143], v[200:203], v[8:11]
	v_mfma_i32_16x16x64_i8 v[64:67], v[128:131], v[204:207], v[64:67]
	v_mfma_i32_16x16x64_i8 v[64:67], v[132:135], v[208:211], v[64:67]
	v_mfma_i32_16x16x64_i8 v[12:15], v[136:139], v[204:207], v[12:15]
	v_mfma_i32_16x16x64_i8 v[12:15], v[140:143], v[208:211], v[12:15]
	s_setprio 0
	s_setprio 1
	v_mfma_i32_16x16x64_i8 v[108:111], v[144:147], v[160:163], v[108:111]
	v_mfma_i32_16x16x64_i8 v[108:111], v[148:151], v[164:167], v[108:111]
	v_mfma_i32_16x16x64_i8 v[44:47], v[152:155], v[160:163], v[44:47]
	v_mfma_i32_16x16x64_i8 v[44:47], v[156:159], v[164:167], v[44:47]
	v_mfma_i32_16x16x64_i8 v[104:107], v[144:147], v[168:171], v[104:107]
	v_mfma_i32_16x16x64_i8 v[104:107], v[148:151], v[192:195], v[104:107]
	v_mfma_i32_16x16x64_i8 v[40:43], v[152:155], v[168:171], v[40:43]
	v_mfma_i32_16x16x64_i8 v[40:43], v[156:159], v[192:195], v[40:43]
	v_mfma_i32_16x16x64_i8 v[100:103], v[144:147], v[196:199], v[100:103]
	v_mfma_i32_16x16x64_i8 v[100:103], v[148:151], v[200:203], v[100:103]
	v_mfma_i32_16x16x64_i8 v[32:35], v[152:155], v[196:199], v[32:35]
	v_mfma_i32_16x16x64_i8 v[32:35], v[156:159], v[200:203], v[32:35]
	s_setprio 2
	s_barrier
	v_mfma_i32_16x16x64_i8 v[76:79], v[144:147], v[204:207], v[76:79]
	ds_read_b128 v[160:163], v189 offset:32768
	ds_read_b128 v[164:167], v189 offset:33792
	v_mfma_i32_16x16x64_i8 v[76:79], v[148:151], v[208:211], v[76:79]
	ds_read_b128 v[168:171], v189 offset:34816
	ds_read_b128 v[192:195], v189 offset:35840
	v_mfma_i32_16x16x64_i8 v[36:39], v[152:155], v[204:207], v[36:39]
	ds_read_b128 v[196:199], v189 offset:36864
	ds_read_b128 v[200:203], v189 offset:37888
	v_mfma_i32_16x16x64_i8 v[36:39], v[156:159], v[208:211], v[36:39]
	s_setprio 0
	s_add_i32 s9, 0, 0x18000
	s_add_i32 s50, 0, 0x1c000
	v_add_u32_e32 v140, s9, v186
	v_add_u32_e32 v156, s50, v186
	ds_read_b128 v[128:131], v140
	ds_read_b128 v[132:135], v140 offset:1024
	ds_read_b128 v[136:139], v140 offset:2048
	ds_read_b128 v[140:143], v140 offset:3072
	ds_read_b128 v[144:147], v156
	ds_read_b128 v[148:151], v156 offset:1024
	ds_read_b128 v[152:155], v156 offset:2048
	ds_read_b128 v[156:159], v156 offset:3072
	s_mov_b32 m0, s71
	ds_read_b128 v[204:207], v189 offset:38912
	ds_read_b128 v[208:211], v189 offset:39936
	s_add_u32 s98, vcc_lo, s38
	s_addc_u32 s99, vcc_hi, s39
	global_load_lds_dwordx4 v172, s[98:99]
	s_mov_b32 m0, s82
	s_nop 0
	s_add_u32 s98, vcc_lo, s40
	s_addc_u32 s99, vcc_hi, s41
	global_load_lds_dwordx4 v172, s[98:99]
	s_waitcnt vmcnt(8)
	s_waitcnt lgkmcnt(0)
	s_barrier
	s_setprio 1
	s_waitcnt lgkmcnt(0)
	v_mfma_i32_16x16x64_i8 v[84:87], v[128:131], v[160:163], v[84:87]
	v_mfma_i32_16x16x64_i8 v[84:87], v[132:135], v[164:167], v[84:87]
	v_mfma_i32_16x16x64_i8 v[16:19], v[136:139], v[160:163], v[16:19]
	v_mfma_i32_16x16x64_i8 v[16:19], v[140:143], v[164:167], v[16:19]
	v_mfma_i32_16x16x64_i8 v[88:91], v[128:131], v[168:171], v[88:91]
	v_mfma_i32_16x16x64_i8 v[88:91], v[132:135], v[192:195], v[88:91]
	v_mfma_i32_16x16x64_i8 v[20:23], v[136:139], v[168:171], v[20:23]
	v_mfma_i32_16x16x64_i8 v[20:23], v[140:143], v[192:195], v[20:23]
	v_mfma_i32_16x16x64_i8 v[92:95], v[128:131], v[196:199], v[92:95]
	v_mfma_i32_16x16x64_i8 v[92:95], v[132:135], v[200:203], v[92:95]
	v_mfma_i32_16x16x64_i8 v[24:27], v[136:139], v[196:199], v[24:27]
	v_mfma_i32_16x16x64_i8 v[24:27], v[140:143], v[200:203], v[24:27]
	v_mfma_i32_16x16x64_i8 v[96:99], v[128:131], v[204:207], v[96:99]
	v_mfma_i32_16x16x64_i8 v[96:99], v[132:135], v[208:211], v[96:99]
	v_mfma_i32_16x16x64_i8 v[28:31], v[136:139], v[204:207], v[28:31]
	v_mfma_i32_16x16x64_i8 v[28:31], v[140:143], v[208:211], v[28:31]
	s_setprio 0
	s_setprio 1
	v_mfma_i32_16x16x64_i8 v[124:127], v[144:147], v[160:163], v[124:127]
	v_mfma_i32_16x16x64_i8 v[124:127], v[148:151], v[164:167], v[124:127]
	v_mfma_i32_16x16x64_i8 v[68:71], v[152:155], v[160:163], v[68:71]
	v_mfma_i32_16x16x64_i8 v[68:71], v[156:159], v[164:167], v[68:71]
	v_mfma_i32_16x16x64_i8 v[120:123], v[144:147], v[168:171], v[120:123]
	v_mfma_i32_16x16x64_i8 v[120:123], v[148:151], v[192:195], v[120:123]
	v_mfma_i32_16x16x64_i8 v[72:75], v[152:155], v[168:171], v[72:75]
	v_mfma_i32_16x16x64_i8 v[72:75], v[156:159], v[192:195], v[72:75]
	v_mfma_i32_16x16x64_i8 v[116:119], v[144:147], v[196:199], v[116:119]
	v_mfma_i32_16x16x64_i8 v[116:119], v[148:151], v[200:203], v[116:119]
	v_mfma_i32_16x16x64_i8 v[80:83], v[152:155], v[196:199], v[80:83]
	v_mfma_i32_16x16x64_i8 v[80:83], v[156:159], v[200:203], v[80:83]
	s_setprio 2
	s_barrier
	v_mfma_i32_16x16x64_i8 v[112:115], v[144:147], v[204:207], v[112:115]
	ds_read_b128 v[160:163], v189 offset:49152
	ds_read_b128 v[164:167], v189 offset:50176
	v_mfma_i32_16x16x64_i8 v[112:115], v[148:151], v[208:211], v[112:115]
	ds_read_b128 v[168:171], v189 offset:51200
	ds_read_b128 v[192:195], v189 offset:52224
	v_mfma_i32_16x16x64_i8 v[60:63], v[152:155], v[204:207], v[60:63]
	ds_read_b128 v[196:199], v189 offset:53248
	ds_read_b128 v[200:203], v189 offset:54272
	v_mfma_i32_16x16x64_i8 v[60:63], v[156:159], v[208:211], v[60:63]
	s_setprio 0
	s_add_i32 s9, s9, s33
	s_mov_b32 m0, s9
	ds_read_b128 v[204:207], v189 offset:55296
	ds_read_b128 v[208:211], v189 offset:56320
	s_add_u32 s98, s100, s44
	s_addc_u32 s99, s101, s45
	global_load_lds_dwordx4 v174, s[98:99]
	s_add_i32 m0, s9, 0x2000
	s_add_i32 s9, s50, s33
	s_add_u32 s98, s100, s46
	s_addc_u32 s99, s101, s47
	global_load_lds_dwordx4 v174, s[98:99]
	s_mov_b32 m0, s9
	s_add_u32 s98, s100, s48
	s_addc_u32 s99, s101, s49
	global_load_lds_dwordx4 v174, s[98:99]
	s_add_i32 m0, s9, 0x2000
	s_nop 0
	s_add_u32 s98, s100, s52
	s_addc_u32 s99, s101, s53
	global_load_lds_dwordx4 v174, s[98:99]
	s_mov_b32 m0, s90
	s_nop 0
	s_add_u32 s98, vcc_lo, s44
	s_addc_u32 s99, vcc_hi, s45
	global_load_lds_dwordx4 v172, s[98:99]
	s_mov_b32 m0, s91
	s_nop 0
	s_add_u32 s98, vcc_lo, s46
	s_addc_u32 s99, vcc_hi, s47
	global_load_lds_dwordx4 v172, s[98:99]
	s_waitcnt vmcnt(8)
	s_waitcnt lgkmcnt(0)
	s_barrier
	s_setprio 1
	s_waitcnt lgkmcnt(0)
	v_mfma_i32_16x16x64_i8 v[48:51], v[128:131], v[160:163], v[48:51]
	v_mfma_i32_16x16x64_i8 v[48:51], v[132:135], v[164:167], v[48:51]
	v_mfma_i32_16x16x64_i8 v[0:3], v[136:139], v[160:163], v[0:3]
	v_mfma_i32_16x16x64_i8 v[0:3], v[140:143], v[164:167], v[0:3]
	v_mfma_i32_16x16x64_i8 v[52:55], v[128:131], v[168:171], v[52:55]
	v_mfma_i32_16x16x64_i8 v[52:55], v[132:135], v[192:195], v[52:55]
	v_mfma_i32_16x16x64_i8 v[4:7], v[136:139], v[168:171], v[4:7]
	v_mfma_i32_16x16x64_i8 v[4:7], v[140:143], v[192:195], v[4:7]
	v_mfma_i32_16x16x64_i8 v[56:59], v[128:131], v[196:199], v[56:59]
	v_mfma_i32_16x16x64_i8 v[56:59], v[132:135], v[200:203], v[56:59]
	v_mfma_i32_16x16x64_i8 v[8:11], v[136:139], v[196:199], v[8:11]
	v_mfma_i32_16x16x64_i8 v[8:11], v[140:143], v[200:203], v[8:11]
	v_mfma_i32_16x16x64_i8 v[64:67], v[128:131], v[204:207], v[64:67]
	v_mfma_i32_16x16x64_i8 v[64:67], v[132:135], v[208:211], v[64:67]
	v_mfma_i32_16x16x64_i8 v[12:15], v[136:139], v[204:207], v[12:15]
	v_mfma_i32_16x16x64_i8 v[12:15], v[140:143], v[208:211], v[12:15]
	s_setprio 0
	s_setprio 1
	v_mfma_i32_16x16x64_i8 v[108:111], v[144:147], v[160:163], v[108:111]
	v_mfma_i32_16x16x64_i8 v[108:111], v[148:151], v[164:167], v[108:111]
	v_mfma_i32_16x16x64_i8 v[44:47], v[152:155], v[160:163], v[44:47]
	v_mfma_i32_16x16x64_i8 v[44:47], v[156:159], v[164:167], v[44:47]
	v_mfma_i32_16x16x64_i8 v[104:107], v[144:147], v[168:171], v[104:107]
	v_mfma_i32_16x16x64_i8 v[104:107], v[148:151], v[192:195], v[104:107]
	v_mfma_i32_16x16x64_i8 v[40:43], v[152:155], v[168:171], v[40:43]
	v_mfma_i32_16x16x64_i8 v[40:43], v[156:159], v[192:195], v[40:43]
	v_mfma_i32_16x16x64_i8 v[100:103], v[144:147], v[196:199], v[100:103]
	v_mfma_i32_16x16x64_i8 v[100:103], v[148:151], v[200:203], v[100:103]
	v_mfma_i32_16x16x64_i8 v[32:35], v[152:155], v[196:199], v[32:35]
	v_mfma_i32_16x16x64_i8 v[32:35], v[156:159], v[200:203], v[32:35]
	s_setprio 2
	s_barrier
	v_mfma_i32_16x16x64_i8 v[76:79], v[144:147], v[204:207], v[76:79]
	v_mfma_i32_16x16x64_i8 v[76:79], v[148:151], v[208:211], v[76:79]
	v_mfma_i32_16x16x64_i8 v[36:39], v[152:155], v[204:207], v[36:39]
	v_mfma_i32_16x16x64_i8 v[36:39], v[156:159], v[208:211], v[36:39]
	s_setprio 0
	s_add_i32 s8, s8, 2
	s_add_u32 s75, s75, 0x100
	s_addc_u32 s78, s78, 0
	s_add_u32 s6, s6, 0x100
	s_addc_u32 s7, s7, 0
	s_cmp_gt_u32 s8, 29
	s_cbranch_scc0 .LBB0_800
	s_and_b64 vcc, exec, s[54:55]
	s_cbranch_vccz .LBB0_803
	s_barrier

.LBB0_1034:
	ds_read_b128 v[138:141], v151
	ds_read_b128 v[142:145], v151 offset:1024
	ds_read_b128 v[146:149], v151 offset:2048
	ds_read_b128 v[154:157], v151 offset:3072
	ds_read_b128 v[158:161], v152
	ds_read_b128 v[162:165], v152 offset:1024
	ds_read_b128 v[166:169], v152 offset:2048
	ds_read_b128 v[170:173], v152 offset:3072
	s_add_u32 s47, s44, 0xffd50080
	s_addc_u32 s64, s45, -1
	s_cmpk_eq_i32 s46, 0xa8
	s_cselect_b32 s65, s5, s64
	s_cselect_b32 s64, s4, s47
	s_cselect_b32 s67, s43, s63
	s_cselect_b32 s66, s42, s62
	s_add_i32 m0, s25, 0xc000
	ds_read_b128 v[174:177], v153
	ds_read_b128 v[178:181], v153 offset:1024
	ds_read_b128 v[182:185], v153 offset:2048
	ds_read_b128 v[186:189], v153 offset:3072
	ds_read_b128 v[190:193], v153 offset:4096
	ds_read_b128 v[194:197], v153 offset:5120
	ds_read_b128 v[198:201], v153 offset:6144
	ds_read_b128 v[202:205], v153 offset:7168
	global_load_lds_dwordx4 v132, s[44:45]
	s_add_i32 m0, s25, 0xe000
	s_nop 0
	s_add_u32 s98, s44, s0
	s_addc_u32 s99, s45, s1
	global_load_lds_dwordx4 v132, s[98:99]
	s_waitcnt vmcnt(8)
	s_waitcnt lgkmcnt(0)
	s_barrier
	s_setprio 1
	s_waitcnt lgkmcnt(0)
	v_mfma_f32_16x16x32_bf16 v[124:127], v[138:141], v[174:177], v[124:127]
	v_mfma_f32_16x16x32_bf16 v[124:127], v[142:145], v[178:181], v[124:127]
	v_mfma_f32_16x16x32_bf16 v[120:123], v[146:149], v[174:177], v[120:123]
	v_mfma_f32_16x16x32_bf16 v[120:123], v[154:157], v[178:181], v[120:123]
	v_mfma_f32_16x16x32_bf16 v[116:119], v[138:141], v[182:185], v[116:119]
	v_mfma_f32_16x16x32_bf16 v[116:119], v[142:145], v[186:189], v[116:119]
	v_mfma_f32_16x16x32_bf16 v[112:115], v[146:149], v[182:185], v[112:115]
	v_mfma_f32_16x16x32_bf16 v[112:115], v[154:157], v[186:189], v[112:115]
	v_mfma_f32_16x16x32_bf16 v[108:111], v[138:141], v[190:193], v[108:111]
	v_mfma_f32_16x16x32_bf16 v[108:111], v[142:145], v[194:197], v[108:111]
	v_mfma_f32_16x16x32_bf16 v[104:107], v[146:149], v[190:193], v[104:107]
	v_mfma_f32_16x16x32_bf16 v[104:107], v[154:157], v[194:197], v[104:107]
	v_mfma_f32_16x16x32_bf16 v[100:103], v[138:141], v[198:201], v[100:103]
	v_mfma_f32_16x16x32_bf16 v[100:103], v[142:145], v[202:205], v[100:103]
	v_mfma_f32_16x16x32_bf16 v[96:99], v[146:149], v[198:201], v[96:99]
	v_mfma_f32_16x16x32_bf16 v[96:99], v[154:157], v[202:205], v[96:99]
	s_setprio 0
	s_setprio 1
	v_mfma_f32_16x16x32_bf16 v[92:95], v[158:161], v[174:177], v[92:95]
	v_mfma_f32_16x16x32_bf16 v[92:95], v[162:165], v[178:181], v[92:95]
	v_mfma_f32_16x16x32_bf16 v[88:91], v[166:169], v[174:177], v[88:91]
	v_mfma_f32_16x16x32_bf16 v[88:91], v[170:173], v[178:181], v[88:91]
	v_mfma_f32_16x16x32_bf16 v[84:87], v[158:161], v[182:185], v[84:87]
	v_mfma_f32_16x16x32_bf16 v[84:87], v[162:165], v[186:189], v[84:87]
	v_mfma_f32_16x16x32_bf16 v[80:83], v[166:169], v[182:185], v[80:83]
	v_mfma_f32_16x16x32_bf16 v[80:83], v[170:173], v[186:189], v[80:83]
	v_mfma_f32_16x16x32_bf16 v[76:79], v[158:161], v[190:193], v[76:79]
	v_mfma_f32_16x16x32_bf16 v[76:79], v[162:165], v[194:197], v[76:79]
	v_mfma_f32_16x16x32_bf16 v[72:75], v[166:169], v[190:193], v[72:75]
	v_mfma_f32_16x16x32_bf16 v[72:75], v[170:173], v[194:197], v[72:75]
	s_setprio 2
	s_barrier
	v_mfma_f32_16x16x32_bf16 v[68:71], v[158:161], v[198:201], v[68:71]
	ds_read_b128 v[174:177], v153 offset:16384
	ds_read_b128 v[178:181], v153 offset:17408
	v_mfma_f32_16x16x32_bf16 v[68:71], v[162:165], v[202:205], v[68:71]
	ds_read_b128 v[182:185], v153 offset:18432
	ds_read_b128 v[186:189], v153 offset:19456
	v_mfma_f32_16x16x32_bf16 v[64:67], v[166:169], v[198:201], v[64:67]
	ds_read_b128 v[190:193], v153 offset:20480
	ds_read_b128 v[194:197], v153 offset:21504
	v_mfma_f32_16x16x32_bf16 v[64:67], v[170:173], v[202:205], v[64:67]
	s_setprio 0
	s_add_i32 s47, s56, s24
	s_mov_b32 m0, s47
	ds_read_b128 v[198:201], v153 offset:22528
	ds_read_b128 v[202:205], v153 offset:23552
	global_load_lds_dwordx4 v130, s[66:67]
	s_add_i32 m0, s47, 0x2000
	s_add_i32 s47, s57, s24
	s_add_u32 s98, s66, s0
	s_addc_u32 s99, s67, s1
	global_load_lds_dwordx4 v130, s[98:99]
	s_mov_b32 m0, s47
	s_nop 0
	s_add_u32 s98, s66, s6
	s_addc_u32 s99, s67, s7
	global_load_lds_dwordx4 v130, s[98:99]
	s_add_i32 m0, s47, 0x2000
	s_nop 0
	s_add_u32 s98, s66, s8
	s_addc_u32 s99, s67, s9
	global_load_lds_dwordx4 v130, s[98:99]
	s_mov_b64 s[100:101], s[64:65]
	s_mov_b32 m0, s25
	s_nop 0
	global_load_lds_dwordx4 v128, s[64:65]
	s_mov_b32 m0, s33
	s_nop 0
	s_add_u32 s98, s64, s0
	s_addc_u32 s99, s65, s1
	global_load_lds_dwordx4 v128, s[98:99]
	s_waitcnt vmcnt(8)
	s_waitcnt lgkmcnt(0)
	s_barrier
	s_setprio 1
	s_waitcnt lgkmcnt(0)
	v_mfma_f32_16x16x32_bf16 v[60:63], v[138:141], v[174:177], v[60:63]
	v_mfma_f32_16x16x32_bf16 v[60:63], v[142:145], v[178:181], v[60:63]
	v_mfma_f32_16x16x32_bf16 v[56:59], v[146:149], v[174:177], v[56:59]
	v_mfma_f32_16x16x32_bf16 v[56:59], v[154:157], v[178:181], v[56:59]
	v_mfma_f32_16x16x32_bf16 v[52:55], v[138:141], v[182:185], v[52:55]
	v_mfma_f32_16x16x32_bf16 v[52:55], v[142:145], v[186:189], v[52:55]
	v_mfma_f32_16x16x32_bf16 v[48:51], v[146:149], v[182:185], v[48:51]
	v_mfma_f32_16x16x32_bf16 v[48:51], v[154:157], v[186:189], v[48:51]
	v_mfma_f32_16x16x32_bf16 v[44:47], v[138:141], v[190:193], v[44:47]
	v_mfma_f32_16x16x32_bf16 v[44:47], v[142:145], v[194:197], v[44:47]
	v_mfma_f32_16x16x32_bf16 v[40:43], v[146:149], v[190:193], v[40:43]
	v_mfma_f32_16x16x32_bf16 v[40:43], v[154:157], v[194:197], v[40:43]
	v_mfma_f32_16x16x32_bf16 v[36:39], v[138:141], v[198:201], v[36:39]
	v_mfma_f32_16x16x32_bf16 v[36:39], v[142:145], v[202:205], v[36:39]
	v_mfma_f32_16x16x32_bf16 v[32:35], v[146:149], v[198:201], v[32:35]
	v_mfma_f32_16x16x32_bf16 v[32:35], v[154:157], v[202:205], v[32:35]
	s_setprio 0
	s_setprio 1
	v_mfma_f32_16x16x32_bf16 v[28:31], v[158:161], v[174:177], v[28:31]
	v_mfma_f32_16x16x32_bf16 v[28:31], v[162:165], v[178:181], v[28:31]
	v_mfma_f32_16x16x32_bf16 v[24:27], v[166:169], v[174:177], v[24:27]
	v_mfma_f32_16x16x32_bf16 v[24:27], v[170:173], v[178:181], v[24:27]
	v_mfma_f32_16x16x32_bf16 v[20:23], v[158:161], v[182:185], v[20:23]
	v_mfma_f32_16x16x32_bf16 v[20:23], v[162:165], v[186:189], v[20:23]
	v_mfma_f32_16x16x32_bf16 v[16:19], v[166:169], v[182:185], v[16:19]
	v_mfma_f32_16x16x32_bf16 v[16:19], v[170:173], v[186:189], v[16:19]
	v_mfma_f32_16x16x32_bf16 v[12:15], v[158:161], v[190:193], v[12:15]
	v_mfma_f32_16x16x32_bf16 v[12:15], v[162:165], v[194:197], v[12:15]
	v_mfma_f32_16x16x32_bf16 v[8:11], v[166:169], v[190:193], v[8:11]
	v_mfma_f32_16x16x32_bf16 v[8:11], v[170:173], v[194:197], v[8:11]
	s_setprio 2
	s_barrier
	v_mfma_f32_16x16x32_bf16 v[4:7], v[158:161], v[198:201], v[4:7]
	ds_read_b128 v[174:177], v153 offset:32768
	ds_read_b128 v[178:181], v153 offset:33792
	v_mfma_f32_16x16x32_bf16 v[4:7], v[162:165], v[202:205], v[4:7]
	ds_read_b128 v[182:185], v153 offset:34816
	ds_read_b128 v[186:189], v153 offset:35840
	v_mfma_f32_16x16x32_bf16 v[0:3], v[166:169], v[198:201], v[0:3]
	ds_read_b128 v[190:193], v153 offset:36864
	ds_read_b128 v[194:197], v153 offset:37888
	v_mfma_f32_16x16x32_bf16 v[0:3], v[170:173], v[202:205], v[0:3]
	s_setprio 0
	s_add_i32 s47, 0, 0x18000
	s_add_i32 s64, 0, 0x1c000
	v_add_u32_e32 v154, s47, v150
	v_add_u32_e32 v170, s64, v150
	ds_read_b128 v[138:141], v154
	ds_read_b128 v[142:145], v154 offset:1024
	ds_read_b128 v[146:149], v154 offset:2048
	ds_read_b128 v[154:157], v154 offset:3072
	ds_read_b128 v[158:161], v170
	ds_read_b128 v[162:165], v170 offset:1024
	ds_read_b128 v[166:169], v170 offset:2048
	ds_read_b128 v[170:173], v170 offset:3072
	s_mov_b32 m0, s48
	ds_read_b128 v[198:201], v153 offset:38912
	ds_read_b128 v[202:205], v153 offset:39936
	s_add_u32 s98, s100, s6
	s_addc_u32 s99, s101, s7
	global_load_lds_dwordx4 v128, s[98:99]
	s_mov_b32 m0, s49
	s_nop 0
	s_add_u32 s98, s100, s8
	s_addc_u32 s99, s101, s9
	global_load_lds_dwordx4 v128, s[98:99]
	s_waitcnt vmcnt(8)
	s_waitcnt lgkmcnt(0)
	s_barrier
	s_setprio 1
	s_waitcnt lgkmcnt(0)
	v_mfma_f32_16x16x32_bf16 v[124:127], v[138:141], v[174:177], v[124:127]
	v_mfma_f32_16x16x32_bf16 v[124:127], v[142:145], v[178:181], v[124:127]
	v_mfma_f32_16x16x32_bf16 v[120:123], v[146:149], v[174:177], v[120:123]
	v_mfma_f32_16x16x32_bf16 v[120:123], v[154:157], v[178:181], v[120:123]
	v_mfma_f32_16x16x32_bf16 v[116:119], v[138:141], v[182:185], v[116:119]
	v_mfma_f32_16x16x32_bf16 v[116:119], v[142:145], v[186:189], v[116:119]
	v_mfma_f32_16x16x32_bf16 v[112:115], v[146:149], v[182:185], v[112:115]
	v_mfma_f32_16x16x32_bf16 v[112:115], v[154:157], v[186:189], v[112:115]
	v_mfma_f32_16x16x32_bf16 v[108:111], v[138:141], v[190:193], v[108:111]
	v_mfma_f32_16x16x32_bf16 v[108:111], v[142:145], v[194:197], v[108:111]
	v_mfma_f32_16x16x32_bf16 v[104:107], v[146:149], v[190:193], v[104:107]
	v_mfma_f32_16x16x32_bf16 v[104:107], v[154:157], v[194:197], v[104:107]
	v_mfma_f32_16x16x32_bf16 v[100:103], v[138:141], v[198:201], v[100:103]
	v_mfma_f32_16x16x32_bf16 v[100:103], v[142:145], v[202:205], v[100:103]
	v_mfma_f32_16x16x32_bf16 v[96:99], v[146:149], v[198:201], v[96:99]
	v_mfma_f32_16x16x32_bf16 v[96:99], v[154:157], v[202:205], v[96:99]
	s_setprio 0
	s_setprio 1
	v_mfma_f32_16x16x32_bf16 v[92:95], v[158:161], v[174:177], v[92:95]
	v_mfma_f32_16x16x32_bf16 v[92:95], v[162:165], v[178:181], v[92:95]
	v_mfma_f32_16x16x32_bf16 v[88:91], v[166:169], v[174:177], v[88:91]
	v_mfma_f32_16x16x32_bf16 v[88:91], v[170:173], v[178:181], v[88:91]
	v_mfma_f32_16x16x32_bf16 v[84:87], v[158:161], v[182:185], v[84:87]
	v_mfma_f32_16x16x32_bf16 v[84:87], v[162:165], v[186:189], v[84:87]
	v_mfma_f32_16x16x32_bf16 v[80:83], v[166:169], v[182:185], v[80:83]
	v_mfma_f32_16x16x32_bf16 v[80:83], v[170:173], v[186:189], v[80:83]
	v_mfma_f32_16x16x32_bf16 v[76:79], v[158:161], v[190:193], v[76:79]
	v_mfma_f32_16x16x32_bf16 v[76:79], v[162:165], v[194:197], v[76:79]
	v_mfma_f32_16x16x32_bf16 v[72:75], v[166:169], v[190:193], v[72:75]
	v_mfma_f32_16x16x32_bf16 v[72:75], v[170:173], v[194:197], v[72:75]
	s_setprio 2
	s_barrier
	v_mfma_f32_16x16x32_bf16 v[68:71], v[158:161], v[198:201], v[68:71]
	ds_read_b128 v[174:177], v153 offset:49152
	ds_read_b128 v[178:181], v153 offset:50176
	v_mfma_f32_16x16x32_bf16 v[68:71], v[162:165], v[202:205], v[68:71]
	ds_read_b128 v[182:185], v153 offset:51200
	ds_read_b128 v[186:189], v153 offset:52224
	v_mfma_f32_16x16x32_bf16 v[64:67], v[166:169], v[198:201], v[64:67]
	ds_read_b128 v[190:193], v153 offset:53248
	ds_read_b128 v[194:197], v153 offset:54272
	v_mfma_f32_16x16x32_bf16 v[64:67], v[170:173], v[202:205], v[64:67]
	s_setprio 0
	s_add_i32 s47, s47, s24
	s_mov_b32 m0, s47
	ds_read_b128 v[198:201], v153 offset:55296
	ds_read_b128 v[202:205], v153 offset:56320
	s_add_u32 s98, s66, s16
	s_addc_u32 s99, s67, s17
	global_load_lds_dwordx4 v130, s[98:99]
	s_add_i32 m0, s47, 0x2000
	s_add_i32 s47, s64, s24
	s_add_u32 s98, s66, s20
	s_addc_u32 s99, s67, s21
	global_load_lds_dwordx4 v130, s[98:99]
	s_mov_b32 m0, s47
	s_add_u32 s98, s66, s34
	s_addc_u32 s99, s67, s35
	global_load_lds_dwordx4 v130, s[98:99]
	s_add_i32 m0, s47, 0x2000
	s_nop 0
	s_add_u32 s98, s66, s36
	s_addc_u32 s99, s67, s37
	global_load_lds_dwordx4 v130, s[98:99]
	s_mov_b32 m0, s51
	s_nop 0
	s_add_u32 s98, s100, s16
	s_addc_u32 s99, s101, s17
	global_load_lds_dwordx4 v128, s[98:99]
	s_mov_b32 m0, s52
	s_nop 0
	s_add_u32 s98, s100, s20
	s_addc_u32 s99, s101, s21
	global_load_lds_dwordx4 v128, s[98:99]
	s_waitcnt vmcnt(8)
	s_waitcnt lgkmcnt(0)
	s_barrier
	s_setprio 1
	s_waitcnt lgkmcnt(0)
	v_mfma_f32_16x16x32_bf16 v[60:63], v[138:141], v[174:177], v[60:63]
	v_mfma_f32_16x16x32_bf16 v[60:63], v[142:145], v[178:181], v[60:63]
	v_mfma_f32_16x16x32_bf16 v[56:59], v[146:149], v[174:177], v[56:59]
	v_mfma_f32_16x16x32_bf16 v[56:59], v[154:157], v[178:181], v[56:59]
	v_mfma_f32_16x16x32_bf16 v[52:55], v[138:141], v[182:185], v[52:55]
	v_mfma_f32_16x16x32_bf16 v[52:55], v[142:145], v[186:189], v[52:55]
	v_mfma_f32_16x16x32_bf16 v[48:51], v[146:149], v[182:185], v[48:51]
	v_mfma_f32_16x16x32_bf16 v[48:51], v[154:157], v[186:189], v[48:51]
	v_mfma_f32_16x16x32_bf16 v[44:47], v[138:141], v[190:193], v[44:47]
	v_mfma_f32_16x16x32_bf16 v[44:47], v[142:145], v[194:197], v[44:47]
	v_mfma_f32_16x16x32_bf16 v[40:43], v[146:149], v[190:193], v[40:43]
	v_mfma_f32_16x16x32_bf16 v[40:43], v[154:157], v[194:197], v[40:43]
	v_mfma_f32_16x16x32_bf16 v[36:39], v[138:141], v[198:201], v[36:39]
	v_mfma_f32_16x16x32_bf16 v[36:39], v[142:145], v[202:205], v[36:39]
	v_mfma_f32_16x16x32_bf16 v[32:35], v[146:149], v[198:201], v[32:35]
	v_mfma_f32_16x16x32_bf16 v[32:35], v[154:157], v[202:205], v[32:35]
	s_setprio 0
	s_setprio 1
	v_mfma_f32_16x16x32_bf16 v[28:31], v[158:161], v[174:177], v[28:31]
	v_mfma_f32_16x16x32_bf16 v[28:31], v[162:165], v[178:181], v[28:31]
	v_mfma_f32_16x16x32_bf16 v[24:27], v[166:169], v[174:177], v[24:27]
	v_mfma_f32_16x16x32_bf16 v[24:27], v[170:173], v[178:181], v[24:27]
	v_mfma_f32_16x16x32_bf16 v[20:23], v[158:161], v[182:185], v[20:23]
	v_mfma_f32_16x16x32_bf16 v[20:23], v[162:165], v[186:189], v[20:23]
	v_mfma_f32_16x16x32_bf16 v[16:19], v[166:169], v[182:185], v[16:19]
	v_mfma_f32_16x16x32_bf16 v[16:19], v[170:173], v[186:189], v[16:19]
	v_mfma_f32_16x16x32_bf16 v[12:15], v[158:161], v[190:193], v[12:15]
	v_mfma_f32_16x16x32_bf16 v[12:15], v[162:165], v[194:197], v[12:15]
	v_mfma_f32_16x16x32_bf16 v[8:11], v[166:169], v[190:193], v[8:11]
	v_mfma_f32_16x16x32_bf16 v[8:11], v[170:173], v[194:197], v[8:11]
	s_setprio 2
	s_barrier
	v_mfma_f32_16x16x32_bf16 v[4:7], v[158:161], v[198:201], v[4:7]
	v_mfma_f32_16x16x32_bf16 v[4:7], v[162:165], v[202:205], v[4:7]
	v_mfma_f32_16x16x32_bf16 v[0:3], v[166:169], v[198:201], v[0:3]
	v_mfma_f32_16x16x32_bf16 v[0:3], v[170:173], v[202:205], v[0:3]
	s_setprio 0
	s_add_i32 s46, s46, 2
	s_add_u32 s62, s62, 0x100
	s_addc_u32 s63, s63, 0
	s_add_u32 s44, s44, 0x100
	s_addc_u32 s45, s45, 0
	s_cmpk_gt_u32 s46, 0xa9
	s_cbranch_scc0 .LBB0_1034
	s_and_b64 vcc, exec, s[38:39]
	s_cbranch_vccz .LBB0_1037
	s_barrier

.LBB0_1180:
	ds_read_b128 v[112:115], v181
	ds_read_b128 v[116:119], v181 offset:1024
	ds_read_b128 v[128:131], v181 offset:2048
	ds_read_b128 v[142:145], v181 offset:3072
	ds_read_b128 v[146:149], v202
	ds_read_b128 v[150:153], v202 offset:1024
	ds_read_b128 v[154:157], v202 offset:2048
	ds_read_b128 v[168:171], v202 offset:3072
	s_add_u32 s49, s46, 0xfff80080
	s_addc_u32 s70, s47, -1
	s_cmp_eq_u32 s48, 28
	s_cselect_b32 s71, s39, s70
	s_cselect_b32 s70, s66, s49
	s_cselect_b32 s73, s37, s69
	s_cselect_b32 s72, s67, s68
	s_add_i32 m0, s45, 0xc000
	ds_read_b128 v[172:175], v203
	ds_read_b128 v[182:185], v203 offset:1024
	ds_read_b128 v[186:189], v203 offset:2048
	ds_read_b128 v[190:193], v203 offset:3072
	ds_read_b128 v[194:197], v203 offset:4096
	ds_read_b128 v[198:201], v203 offset:5120
	ds_read_b128 v[206:209], v203 offset:6144
	ds_read_b128 v[210:213], v203 offset:7168
	global_load_lds_dwordx4 v162, s[46:47]
	s_add_i32 m0, s45, 0xe000
	s_nop 0
	s_add_u32 s98, s46, s2
	s_addc_u32 s99, s47, s3
	global_load_lds_dwordx4 v162, s[98:99]
	s_waitcnt vmcnt(8)
	s_waitcnt lgkmcnt(0)
	s_barrier
	s_setprio 1
	s_waitcnt lgkmcnt(0)
	v_mfma_i32_16x16x64_i8 v[138:141], v[112:115], v[172:175], v[138:141]
	v_mfma_i32_16x16x64_i8 v[132:135], v[128:131], v[172:175], v[134:137]
	v_mfma_i32_16x16x64_i8 v[124:127], v[112:115], v[186:189], v[124:127]
	v_mfma_i32_16x16x64_i8 v[120:123], v[128:131], v[186:189], v[120:123]
	v_mfma_i32_16x16x64_i8 v[108:111], v[112:115], v[194:197], v[108:111]
	v_mfma_i32_16x16x64_i8 v[104:107], v[128:131], v[194:197], v[104:107]
	v_mfma_i32_16x16x64_i8 v[100:103], v[112:115], v[206:209], v[100:103]
	v_mfma_i32_16x16x64_i8 v[96:99], v[128:131], v[206:209], v[96:99]
	v_mfma_i32_16x16x64_i8 v[138:141], v[116:119], v[182:185], v[138:141]
	v_mfma_i32_16x16x64_i8 v[132:135], v[142:145], v[182:185], v[132:135]
	v_mfma_i32_16x16x64_i8 v[124:127], v[116:119], v[190:193], v[124:127]
	v_mfma_i32_16x16x64_i8 v[120:123], v[142:145], v[190:193], v[120:123]
	v_mfma_i32_16x16x64_i8 v[108:111], v[116:119], v[198:201], v[108:111]
	v_mfma_i32_16x16x64_i8 v[104:107], v[142:145], v[198:201], v[104:107]
	v_mfma_i32_16x16x64_i8 v[100:103], v[116:119], v[210:213], v[100:103]
	v_mfma_i32_16x16x64_i8 v[96:99], v[142:145], v[210:213], v[96:99]
	s_setprio 0
	s_setprio 1
	v_mfma_i32_16x16x64_i8 v[60:63], v[146:149], v[172:175], v[60:63]
	v_mfma_i32_16x16x64_i8 v[60:63], v[150:153], v[182:185], v[60:63]
	v_mfma_i32_16x16x64_i8 v[56:59], v[154:157], v[172:175], v[56:59]
	v_mfma_i32_16x16x64_i8 v[56:59], v[168:171], v[182:185], v[56:59]
	v_mfma_i32_16x16x64_i8 v[52:55], v[146:149], v[186:189], v[52:55]
	v_mfma_i32_16x16x64_i8 v[52:55], v[150:153], v[190:193], v[52:55]
	v_mfma_i32_16x16x64_i8 v[48:51], v[154:157], v[186:189], v[48:51]
	v_mfma_i32_16x16x64_i8 v[48:51], v[168:171], v[190:193], v[48:51]
	v_mfma_i32_16x16x64_i8 v[44:47], v[146:149], v[194:197], v[44:47]
	v_mfma_i32_16x16x64_i8 v[44:47], v[150:153], v[198:201], v[44:47]
	v_mfma_i32_16x16x64_i8 v[40:43], v[154:157], v[194:197], v[40:43]
	v_mfma_i32_16x16x64_i8 v[40:43], v[168:171], v[198:201], v[40:43]
	s_setprio 2
	s_barrier
	v_mfma_i32_16x16x64_i8 v[36:39], v[146:149], v[206:209], v[36:39]
	ds_read_b128 v[172:175], v203 offset:16384
	ds_read_b128 v[182:185], v203 offset:17408
	v_mfma_i32_16x16x64_i8 v[36:39], v[150:153], v[210:213], v[36:39]
	ds_read_b128 v[186:189], v203 offset:18432
	ds_read_b128 v[190:193], v203 offset:19456
	v_mfma_i32_16x16x64_i8 v[32:35], v[154:157], v[206:209], v[32:35]
	ds_read_b128 v[194:197], v203 offset:20480
	ds_read_b128 v[198:201], v203 offset:21504
	v_mfma_i32_16x16x64_i8 v[32:35], v[168:171], v[210:213], v[32:35]
	s_setprio 0
	s_add_i32 s49, s61, s33
	s_mov_b32 m0, s49
	ds_read_b128 v[206:209], v203 offset:22528
	ds_read_b128 v[210:213], v203 offset:23552
	global_load_lds_dwordx4 v160, s[72:73]
	s_add_i32 m0, s49, 0x2000
	s_add_i32 s49, s62, s33
	s_add_u32 s98, s72, s2
	s_addc_u32 s99, s73, s3
	global_load_lds_dwordx4 v160, s[98:99]
	s_mov_b32 m0, s49
	s_mov_b64 s[100:101], s[70:71]
	s_add_u32 s98, s72, s6
	s_addc_u32 s99, s73, s7
	global_load_lds_dwordx4 v160, s[98:99]
	s_add_i32 m0, s49, 0x2000
	s_nop 0
	s_add_u32 s98, s72, s8
	s_addc_u32 s99, s73, s9
	global_load_lds_dwordx4 v160, s[98:99]
	s_mov_b32 m0, s45
	s_nop 0
	global_load_lds_dwordx4 v158, s[70:71]
	s_mov_b32 m0, s50
	s_nop 0
	s_add_u32 s98, s70, s2
	s_addc_u32 s99, s71, s3
	global_load_lds_dwordx4 v158, s[98:99]
	s_waitcnt vmcnt(8)
	s_waitcnt lgkmcnt(0)
	s_barrier
	s_setprio 1
	s_waitcnt lgkmcnt(0)
	v_mfma_i32_16x16x64_i8 v[92:95], v[112:115], v[172:175], v[92:95]
	v_mfma_i32_16x16x64_i8 v[92:95], v[116:119], v[182:185], v[92:95]
	v_mfma_i32_16x16x64_i8 v[88:91], v[128:131], v[172:175], v[88:91]
	v_mfma_i32_16x16x64_i8 v[88:91], v[142:145], v[182:185], v[88:91]
	v_mfma_i32_16x16x64_i8 v[84:87], v[112:115], v[186:189], v[84:87]
	v_mfma_i32_16x16x64_i8 v[84:87], v[116:119], v[190:193], v[84:87]
	v_mfma_i32_16x16x64_i8 v[80:83], v[128:131], v[186:189], v[80:83]
	v_mfma_i32_16x16x64_i8 v[80:83], v[142:145], v[190:193], v[80:83]
	v_mfma_i32_16x16x64_i8 v[76:79], v[112:115], v[194:197], v[76:79]
	v_mfma_i32_16x16x64_i8 v[76:79], v[116:119], v[198:201], v[76:79]
	v_mfma_i32_16x16x64_i8 v[72:75], v[128:131], v[194:197], v[72:75]
	v_mfma_i32_16x16x64_i8 v[72:75], v[142:145], v[198:201], v[72:75]
	v_mfma_i32_16x16x64_i8 v[68:71], v[112:115], v[206:209], v[68:71]
	v_mfma_i32_16x16x64_i8 v[68:71], v[116:119], v[210:213], v[68:71]
	v_mfma_i32_16x16x64_i8 v[64:67], v[128:131], v[206:209], v[64:67]
	v_mfma_i32_16x16x64_i8 v[64:67], v[142:145], v[210:213], v[64:67]
	s_setprio 0
	s_setprio 1
	v_mfma_i32_16x16x64_i8 v[28:31], v[146:149], v[172:175], v[28:31]
	v_mfma_i32_16x16x64_i8 v[28:31], v[150:153], v[182:185], v[28:31]
	v_mfma_i32_16x16x64_i8 v[24:27], v[154:157], v[172:175], v[24:27]
	v_mfma_i32_16x16x64_i8 v[24:27], v[168:171], v[182:185], v[24:27]
	v_mfma_i32_16x16x64_i8 v[20:23], v[146:149], v[186:189], v[20:23]
	v_mfma_i32_16x16x64_i8 v[20:23], v[150:153], v[190:193], v[20:23]
	v_mfma_i32_16x16x64_i8 v[16:19], v[154:157], v[186:189], v[16:19]
	v_mfma_i32_16x16x64_i8 v[16:19], v[168:171], v[190:193], v[16:19]
	v_mfma_i32_16x16x64_i8 v[12:15], v[146:149], v[194:197], v[12:15]
	v_mfma_i32_16x16x64_i8 v[12:15], v[150:153], v[198:201], v[12:15]
	v_mfma_i32_16x16x64_i8 v[8:11], v[154:157], v[194:197], v[8:11]
	v_mfma_i32_16x16x64_i8 v[8:11], v[168:171], v[198:201], v[8:11]
	s_setprio 2
	s_barrier
	v_mfma_i32_16x16x64_i8 v[4:7], v[146:149], v[206:209], v[4:7]
	ds_read_b128 v[172:175], v203 offset:32768
	ds_read_b128 v[182:185], v203 offset:33792
	v_mfma_i32_16x16x64_i8 v[4:7], v[150:153], v[210:213], v[4:7]
	ds_read_b128 v[186:189], v203 offset:34816
	ds_read_b128 v[190:193], v203 offset:35840
	v_mfma_i32_16x16x64_i8 v[0:3], v[154:157], v[206:209], v[0:3]
	ds_read_b128 v[194:197], v203 offset:36864
	ds_read_b128 v[198:201], v203 offset:37888
	v_mfma_i32_16x16x64_i8 v[0:3], v[168:171], v[210:213], v[0:3]
	s_setprio 0
	s_add_i32 s49, 0, 0x18000
	v_add_u32_e32 v136, s49, v179
	s_add_i32 s70, 0, 0x1c000
	ds_read_b128 v[112:115], v136
	ds_read_b128 v[116:119], v136 offset:1024
	ds_read_b128 v[128:131], v136 offset:2048
	ds_read_b128 v[142:145], v136 offset:3072
	v_add_u32_e32 v136, s70, v179
	ds_read_b128 v[146:149], v136
	ds_read_b128 v[150:153], v136 offset:1024
	ds_read_b128 v[154:157], v136 offset:2048
	ds_read_b128 v[168:171], v136 offset:3072
	s_mov_b32 m0, s51
	ds_read_b128 v[206:209], v203 offset:38912
	ds_read_b128 v[210:213], v203 offset:39936
	s_add_u32 s98, s100, s6
	s_addc_u32 s99, s101, s7
	global_load_lds_dwordx4 v158, s[98:99]
	s_mov_b32 m0, s52
	s_nop 0
	s_add_u32 s98, s100, s8
	s_addc_u32 s99, s101, s9
	global_load_lds_dwordx4 v158, s[98:99]
	s_waitcnt vmcnt(8)
	s_waitcnt lgkmcnt(0)
	s_barrier
	s_setprio 1
	s_waitcnt lgkmcnt(0)
	v_mfma_i32_16x16x64_i8 v[136:139], v[112:115], v[172:175], v[138:141]
	v_mfma_i32_16x16x64_i8 v[132:135], v[128:131], v[172:175], v[132:135]
	v_mfma_i32_16x16x64_i8 v[124:127], v[112:115], v[186:189], v[124:127]
	v_mfma_i32_16x16x64_i8 v[120:123], v[128:131], v[186:189], v[120:123]
	v_mfma_i32_16x16x64_i8 v[108:111], v[112:115], v[194:197], v[108:111]
	v_mfma_i32_16x16x64_i8 v[104:107], v[128:131], v[194:197], v[104:107]
	v_mfma_i32_16x16x64_i8 v[100:103], v[112:115], v[206:209], v[100:103]
	v_mfma_i32_16x16x64_i8 v[96:99], v[128:131], v[206:209], v[96:99]
	v_mfma_i32_16x16x64_i8 v[138:141], v[116:119], v[182:185], v[136:139]
	v_mfma_i32_16x16x64_i8 v[134:137], v[142:145], v[182:185], v[132:135]
	v_mfma_i32_16x16x64_i8 v[124:127], v[116:119], v[190:193], v[124:127]
	v_mfma_i32_16x16x64_i8 v[120:123], v[142:145], v[190:193], v[120:123]
	v_mfma_i32_16x16x64_i8 v[108:111], v[116:119], v[198:201], v[108:111]
	v_mfma_i32_16x16x64_i8 v[104:107], v[142:145], v[198:201], v[104:107]
	v_mfma_i32_16x16x64_i8 v[100:103], v[116:119], v[210:213], v[100:103]
	v_mfma_i32_16x16x64_i8 v[96:99], v[142:145], v[210:213], v[96:99]
	s_setprio 0
	s_setprio 1
	v_mfma_i32_16x16x64_i8 v[60:63], v[146:149], v[172:175], v[60:63]
	v_mfma_i32_16x16x64_i8 v[60:63], v[150:153], v[182:185], v[60:63]
	v_mfma_i32_16x16x64_i8 v[56:59], v[154:157], v[172:175], v[56:59]
	v_mfma_i32_16x16x64_i8 v[56:59], v[168:171], v[182:185], v[56:59]
	v_mfma_i32_16x16x64_i8 v[52:55], v[146:149], v[186:189], v[52:55]
	v_mfma_i32_16x16x64_i8 v[52:55], v[150:153], v[190:193], v[52:55]
	v_mfma_i32_16x16x64_i8 v[48:51], v[154:157], v[186:189], v[48:51]
	v_mfma_i32_16x16x64_i8 v[48:51], v[168:171], v[190:193], v[48:51]
	v_mfma_i32_16x16x64_i8 v[44:47], v[146:149], v[194:197], v[44:47]
	v_mfma_i32_16x16x64_i8 v[44:47], v[150:153], v[198:201], v[44:47]
	v_mfma_i32_16x16x64_i8 v[40:43], v[154:157], v[194:197], v[40:43]
	v_mfma_i32_16x16x64_i8 v[40:43], v[168:171], v[198:201], v[40:43]
	s_setprio 2
	s_barrier
	v_mfma_i32_16x16x64_i8 v[36:39], v[146:149], v[206:209], v[36:39]
	ds_read_b128 v[172:175], v203 offset:49152
	ds_read_b128 v[182:185], v203 offset:50176
	v_mfma_i32_16x16x64_i8 v[36:39], v[150:153], v[210:213], v[36:39]
	ds_read_b128 v[186:189], v203 offset:51200
	ds_read_b128 v[190:193], v203 offset:52224
	v_mfma_i32_16x16x64_i8 v[32:35], v[154:157], v[206:209], v[32:35]
	ds_read_b128 v[194:197], v203 offset:53248
	ds_read_b128 v[198:201], v203 offset:54272
	v_mfma_i32_16x16x64_i8 v[32:35], v[168:171], v[210:213], v[32:35]
	s_setprio 0
	s_add_i32 s49, s49, s33
	s_mov_b32 m0, s49
	ds_read_b128 v[206:209], v203 offset:55296
	ds_read_b128 v[210:213], v203 offset:56320
	s_add_u32 s98, s72, s16
	s_addc_u32 s99, s73, s17
	global_load_lds_dwordx4 v160, s[98:99]
	s_add_i32 m0, s49, 0x2000
	s_add_i32 s49, s70, s33
	s_add_u32 s98, s72, s18
	s_addc_u32 s99, s73, s19
	global_load_lds_dwordx4 v160, s[98:99]
	s_mov_b32 m0, s49
	s_nop 0
	s_add_u32 s98, s72, s20
	s_addc_u32 s99, s73, s21
	global_load_lds_dwordx4 v160, s[98:99]
	s_add_i32 m0, s49, 0x2000
	s_nop 0
	s_add_u32 s98, s72, s30
	s_addc_u32 s99, s73, s31
	global_load_lds_dwordx4 v160, s[98:99]
	s_mov_b32 m0, s54
	s_nop 0
	s_add_u32 s98, s100, s16
	s_addc_u32 s99, s101, s17
	global_load_lds_dwordx4 v158, s[98:99]
	s_mov_b32 m0, s55
	s_nop 0
	s_add_u32 s98, s100, s18
	s_addc_u32 s99, s101, s19
	global_load_lds_dwordx4 v158, s[98:99]
	s_waitcnt vmcnt(8)
	s_waitcnt lgkmcnt(0)
	s_barrier
	s_setprio 1
	s_waitcnt lgkmcnt(0)
	v_mfma_i32_16x16x64_i8 v[92:95], v[112:115], v[172:175], v[92:95]
	v_mfma_i32_16x16x64_i8 v[92:95], v[116:119], v[182:185], v[92:95]
	v_mfma_i32_16x16x64_i8 v[88:91], v[128:131], v[172:175], v[88:91]
	v_mfma_i32_16x16x64_i8 v[88:91], v[142:145], v[182:185], v[88:91]
	v_mfma_i32_16x16x64_i8 v[84:87], v[112:115], v[186:189], v[84:87]
	v_mfma_i32_16x16x64_i8 v[84:87], v[116:119], v[190:193], v[84:87]
	v_mfma_i32_16x16x64_i8 v[80:83], v[128:131], v[186:189], v[80:83]
	v_mfma_i32_16x16x64_i8 v[80:83], v[142:145], v[190:193], v[80:83]
	v_mfma_i32_16x16x64_i8 v[76:79], v[112:115], v[194:197], v[76:79]
	v_mfma_i32_16x16x64_i8 v[76:79], v[116:119], v[198:201], v[76:79]
	v_mfma_i32_16x16x64_i8 v[72:75], v[128:131], v[194:197], v[72:75]
	v_mfma_i32_16x16x64_i8 v[72:75], v[142:145], v[198:201], v[72:75]
	v_mfma_i32_16x16x64_i8 v[68:71], v[112:115], v[206:209], v[68:71]
	v_mfma_i32_16x16x64_i8 v[68:71], v[116:119], v[210:213], v[68:71]
	v_mfma_i32_16x16x64_i8 v[64:67], v[128:131], v[206:209], v[64:67]
	v_mfma_i32_16x16x64_i8 v[64:67], v[142:145], v[210:213], v[64:67]
	s_setprio 0
	s_setprio 1
	v_mfma_i32_16x16x64_i8 v[28:31], v[146:149], v[172:175], v[28:31]
	v_mfma_i32_16x16x64_i8 v[28:31], v[150:153], v[182:185], v[28:31]
	v_mfma_i32_16x16x64_i8 v[24:27], v[154:157], v[172:175], v[24:27]
	v_mfma_i32_16x16x64_i8 v[24:27], v[168:171], v[182:185], v[24:27]
	v_mfma_i32_16x16x64_i8 v[20:23], v[146:149], v[186:189], v[20:23]
	v_mfma_i32_16x16x64_i8 v[20:23], v[150:153], v[190:193], v[20:23]
	v_mfma_i32_16x16x64_i8 v[16:19], v[154:157], v[186:189], v[16:19]
	v_mfma_i32_16x16x64_i8 v[16:19], v[168:171], v[190:193], v[16:19]
	v_mfma_i32_16x16x64_i8 v[12:15], v[146:149], v[194:197], v[12:15]
	v_mfma_i32_16x16x64_i8 v[12:15], v[150:153], v[198:201], v[12:15]
	v_mfma_i32_16x16x64_i8 v[8:11], v[154:157], v[194:197], v[8:11]
	v_mfma_i32_16x16x64_i8 v[8:11], v[168:171], v[198:201], v[8:11]
	s_setprio 2
	s_barrier
	v_mfma_i32_16x16x64_i8 v[4:7], v[146:149], v[206:209], v[4:7]
	v_mfma_i32_16x16x64_i8 v[4:7], v[150:153], v[210:213], v[4:7]
	v_mfma_i32_16x16x64_i8 v[0:3], v[154:157], v[206:209], v[0:3]
	v_mfma_i32_16x16x64_i8 v[0:3], v[168:171], v[210:213], v[0:3]
	s_setprio 0
	s_add_i32 s48, s48, 2
	s_add_u32 s68, s68, 0x100
	s_addc_u32 s69, s69, 0
	s_add_u32 s46, s46, 0x100
	s_addc_u32 s47, s47, 0
	s_cmp_gt_u32 s48, 29
	s_cbranch_scc0 .LBB0_1180
	s_and_b64 vcc, exec, s[34:35]
	s_cbranch_vccz .LBB0_1183
	s_barrier
